# adds hand-written packed-f32 fast path for prompt conv+gelu items in P6 (bit-identical math, SGPR addressing, counted waits)
# baseline (speedup 1.0000x reference)
; __device__ __forceinline__ float bf2f(unsigned b) { return __uint_as_float(b << 16); }
; __device__ __forceinline__ void act_item(int item, u16* UP, const u16* HALO, const float* sconv, const float* wconv, const float* bconv, float* out, int lane) {
;     ...
;     const bool sample = rb >= 256;
;     float g2[2] = {0.f, 0.f}, g1[2] = {0.f, 0.f}, v2[2] = {0.f, 0.f}, v1[2] = {0.f, 0.f};
;     if (!sample && (rb & 31) != 0) {
;         const unsigned a = *(const unsigned*)(HALO + (size_t)((rb - 1) * 2) * FF2 + j0), b = *(const unsigned*)(HALO + (size_t)((rb - 1) * 2) * FF2 + FF + j0);
;         const unsigned c = *(const unsigned*)(HALO + (size_t)((rb - 1) * 2 + 1) * FF2 + j0), dd = *(const unsigned*)(HALO + (size_t)((rb - 1) * 2 + 1) * FF2 + FF + j0);
;         g2[0] = bf2f(a & 0xffffu); g2[1] = bf2f(a >> 16); v2[0] = bf2f(b & 0xffffu); v2[1] = bf2f(b >> 16);
;         g1[0] = bf2f(c & 0xffffu); g1[1] = bf2f(c >> 16); v1[0] = bf2f(dd & 0xffffu); v1[1] = bf2f(dd >> 16);
;     }
;     for (int tb = 0; tb < 64; tb += 16) {
;         unsigned gw[16], vw[16];
; #pragma unroll
;         for (int t = 0; t < 16; ++t) { const size_t row = (size_t)rb * 64 + tb + t; gw[t] = *(const unsigned*)(UP + row * FF2 + j0); vw[t] = *(const unsigned*)(UP + row * FF2 + FF + j0); }
; #pragma unroll
;         for (int t = 0; t < 16; ++t) {
;             const int row = rb * 64 + tb + t;
;             if (sample && (t & 3) == 0) { const int ns = (row - TP) >> 2; const float* s0 = sconv + (size_t)ns * 2 * FF2;
;                 const f32x2 a = *(const f32x2*)(s0 + j0), b = *(const f32x2*)(s0 + FF + j0), c = *(const f32x2*)(s0 + FF2 + j0), dd = *(const f32x2*)(s0 + FF2 + FF + j0);
;                 g2[0] = a.x; g2[1] = a.y; v2[0] = b.x; v2[1] = b.y; g1[0] = c.x; g1[1] = c.y; v1[0] = dd.x; v1[1] = dd.y; }
;             const float g0[2] = {bf2f(gw[t] & 0xffffu), bf2f(gw[t] >> 16)}, v0[2] = {bf2f(vw[t] & 0xffffu), bf2f(vw[t] >> 16)};
;             float res[2];
; #pragma unroll
;             for (int p = 0; p < 2; ++p) { const float cgv = bg[p] + wgt[0][p] * g2[p] + wgt[1][p] * g1[p] + wgt[2][p] * g0[p];
;                 const float cvv = bv[p] + wvl[0][p] * v2[p] + wvl[1][p] * v1[p] + wvl[2][p] * v0[p]; res[p] = gelu_t(cgv) * cvv;
;                 g2[p] = g1[p]; g1[p] = g0[p]; v2[p] = v1[p]; v1[p] = v0[p]; }
;             *(unsigned*)(UP + (size_t)row * FF2 + j0) = pk2(res[0], res[1]);
.Lact_fast:
	v_lshlrev_b32_e32 v2, 1, v2
	v_add_u32_e32 v3, 0x1600, v2
	v_lshlrev_b32_e32 v1, 1, v2
	s_mul_i32 s6, s0, 0xb0000
	s_mul_hi_u32 s7, s0, 0xb0000
	s_add_u32 s64, s92, s6
	s_addc_u32 s65, s93, s7
	s_add_u32 s64, s64, 0x4300000
	s_addc_u32 s65, s65, 0
	s_mov_b64 s[66:67], s[64:65]
	s_mov_b32 s58, 0x3d372713
	s_mov_b32 s59, s58
	s_mov_b32 s60, 0xbfcc422a
	s_mov_b32 s61, s60
	s_mov_b32 s68, 0x3fb8aa3b
	s_mov_b32 s69, s68
	s_mov_b32 s82, 1.0
	s_mov_b32 s83, 1.0
	s_and_b32 s1, s0, 31
	s_cmp_eq_u32 s1, 0
	s_cbranch_scc1 .Lact_nohalo
	s_mul_i32 s6, s0, 0x5800
	s_mul_hi_u32 s7, s0, 0x5800
	s_add_u32 s6, s18, s6
	s_addc_u32 s7, s19, s7
	s_sub_u32 s6, s6, 0x5800
	s_subb_u32 s7, s7, 0
	global_load_dword v192, v2, s[6:7]
	global_load_dword v193, v3, s[6:7]
	s_add_u32 s6, s6, 0x2c00
	s_addc_u32 s7, s7, 0
	global_load_dword v194, v2, s[6:7]
	global_load_dword v195, v3, s[6:7]
	s_branch .Lact_rows
.Lact_nohalo:
	v_mov_b32_e32 v192, 0
	v_mov_b32_e32 v193, 0
	v_mov_b32_e32 v194, 0
	v_mov_b32_e32 v195, 0
.Lact_rows:
	global_load_dword v160, v2, s[64:65]
	global_load_dword v161, v3, s[64:65]
	s_add_u32 s64, s64, 0x2c00
	s_addc_u32 s65, s65, 0
	global_load_dword v162, v2, s[64:65]
	global_load_dword v163, v3, s[64:65]
	s_add_u32 s64, s64, 0x2c00
	s_addc_u32 s65, s65, 0
	global_load_dword v164, v2, s[64:65]
	global_load_dword v165, v3, s[64:65]
	s_add_u32 s64, s64, 0x2c00
	s_addc_u32 s65, s65, 0
	global_load_dword v166, v2, s[64:65]
	global_load_dword v167, v3, s[64:65]
	s_add_u32 s64, s64, 0x2c00
	s_addc_u32 s65, s65, 0
	global_load_dword v168, v2, s[64:65]
	global_load_dword v169, v3, s[64:65]
	s_add_u32 s64, s64, 0x2c00
	s_addc_u32 s65, s65, 0
	global_load_dword v170, v2, s[64:65]
	global_load_dword v171, v3, s[64:65]
	s_add_u32 s64, s64, 0x2c00
	s_addc_u32 s65, s65, 0
	global_load_dword v172, v2, s[64:65]
	global_load_dword v173, v3, s[64:65]
	s_add_u32 s64, s64, 0x2c00
	s_addc_u32 s65, s65, 0
	global_load_dword v174, v2, s[64:65]
	global_load_dword v175, v3, s[64:65]
	s_add_u32 s64, s64, 0x2c00
	s_addc_u32 s65, s65, 0
	global_load_dword v176, v2, s[64:65]
	global_load_dword v177, v3, s[64:65]
	s_add_u32 s64, s64, 0x2c00
	s_addc_u32 s65, s65, 0
	global_load_dword v178, v2, s[64:65]
	global_load_dword v179, v3, s[64:65]
	s_add_u32 s64, s64, 0x2c00
	s_addc_u32 s65, s65, 0
	global_load_dword v180, v2, s[64:65]
	global_load_dword v181, v3, s[64:65]
	s_add_u32 s64, s64, 0x2c00
	s_addc_u32 s65, s65, 0
	global_load_dword v182, v2, s[64:65]
	global_load_dword v183, v3, s[64:65]
	s_add_u32 s64, s64, 0x2c00
	s_addc_u32 s65, s65, 0
	global_load_dword v184, v2, s[64:65]
	global_load_dword v185, v3, s[64:65]
	s_add_u32 s64, s64, 0x2c00
	s_addc_u32 s65, s65, 0
	global_load_dword v186, v2, s[64:65]
	global_load_dword v187, v3, s[64:65]
	s_add_u32 s64, s64, 0x2c00
	s_addc_u32 s65, s65, 0
	global_load_dword v188, v2, s[64:65]
	global_load_dword v189, v3, s[64:65]
	s_add_u32 s64, s64, 0x2c00
	s_addc_u32 s65, s65, 0
	global_load_dword v190, v2, s[64:65]
	global_load_dword v191, v3, s[64:65]
	s_add_u32 s64, s64, 0x2c00
	s_addc_u32 s65, s65, 0
	s_waitcnt vmcnt(30)
	v_lshlrev_b32_e32 v200, 16, v192
	v_and_b32_e32 v201, 0xffff0000, v192
	v_lshlrev_b32_e32 v202, 16, v193
	v_and_b32_e32 v203, 0xffff0000, v193
	v_lshlrev_b32_e32 v204, 16, v194
	v_and_b32_e32 v205, 0xffff0000, v194
	v_lshlrev_b32_e32 v206, 16, v195
	v_and_b32_e32 v207, 0xffff0000, v195
	v_lshlrev_b32_e32 v196, 16, v160
	v_and_b32_e32 v197, 0xffff0000, v160
	v_lshlrev_b32_e32 v198, 16, v161
	v_and_b32_e32 v199, 0xffff0000, v161
	v_pk_fma_f32 v[208:209], v[4:5], v[200:201], v[16:17]
	v_pk_fma_f32 v[210:211], v[6:7], v[202:203], v[18:19]
	v_pk_fma_f32 v[208:209], v[8:9], v[204:205], v[208:209]
	v_pk_fma_f32 v[210:211], v[10:11], v[206:207], v[210:211]
	v_pk_fma_f32 v[208:209], v[12:13], v[196:197], v[208:209]
	v_pk_fma_f32 v[210:211], v[14:15], v[198:199], v[210:211]
	v_pk_mul_f32 v[212:213], v[208:209], s[58:59]
	v_pk_mul_f32 v[212:213], v[208:209], v[212:213]
	v_pk_fma_f32 v[212:213], v[208:209], v[212:213], v[208:209]
	v_pk_mul_f32 v[212:213], v[212:213], s[60:61]
	v_pk_mul_f32 v[212:213], v[212:213], s[68:69]
	v_exp_f32_e32 v214, v212
	v_exp_f32_e32 v215, v213
	s_nop 0
	v_pk_add_f32 v[214:215], v[214:215], s[82:83]
	v_rcp_f32_e32 v214, v214
	v_rcp_f32_e32 v215, v215
	s_nop 0
	v_pk_mul_f32 v[212:213], v[208:209], v[214:215]
	v_pk_mul_f32 v[212:213], v[210:211], v[212:213]
	v_cvt_pk_bf16_f32 v216, v212, v213
	global_store_dword v2, v216, s[66:67]
	s_add_u32 s66, s66, 0x2c00
	s_addc_u32 s67, s67, 0
	s_waitcnt vmcnt(29)
	v_lshlrev_b32_e32 v200, 16, v162
	v_and_b32_e32 v201, 0xffff0000, v162
	v_lshlrev_b32_e32 v202, 16, v163
	v_and_b32_e32 v203, 0xffff0000, v163
	v_pk_fma_f32 v[208:209], v[4:5], v[204:205], v[16:17]
	v_pk_fma_f32 v[210:211], v[6:7], v[206:207], v[18:19]
	v_pk_fma_f32 v[208:209], v[8:9], v[196:197], v[208:209]
	v_pk_fma_f32 v[210:211], v[10:11], v[198:199], v[210:211]
	v_pk_fma_f32 v[208:209], v[12:13], v[200:201], v[208:209]
	v_pk_fma_f32 v[210:211], v[14:15], v[202:203], v[210:211]
	v_pk_mul_f32 v[212:213], v[208:209], s[58:59]
	v_pk_mul_f32 v[212:213], v[208:209], v[212:213]
	v_pk_fma_f32 v[212:213], v[208:209], v[212:213], v[208:209]
	v_pk_mul_f32 v[212:213], v[212:213], s[60:61]
	v_pk_mul_f32 v[212:213], v[212:213], s[68:69]
	v_exp_f32_e32 v214, v212
	v_exp_f32_e32 v215, v213
	s_nop 0
	v_pk_add_f32 v[214:215], v[214:215], s[82:83]
	v_rcp_f32_e32 v214, v214
	v_rcp_f32_e32 v215, v215
	s_nop 0
	v_pk_mul_f32 v[212:213], v[208:209], v[214:215]
	v_pk_mul_f32 v[212:213], v[210:211], v[212:213]
	v_cvt_pk_bf16_f32 v216, v212, v213
	global_store_dword v2, v216, s[66:67]
	s_add_u32 s66, s66, 0x2c00
	s_addc_u32 s67, s67, 0
	s_waitcnt vmcnt(28)
; __device__ __forceinline__ float bf2f(unsigned b) { return __uint_as_float(b << 16); }
; __device__ __forceinline__ unsigned pk2(float lo, float hi) { unsigned r; asm("v_cvt_pk_bf16_f32 %0, %1, %2" : "=v"(r) : "v"(lo), "v"(hi)); return r; }
; __device__ __forceinline__ float gelu_t(float x) { return x * __builtin_amdgcn_rcpf(1.f + __expf(-1.5957691216057308f * (x + 0.044715f * x * x * x))); }
; __device__ __forceinline__ void act_item(int item, u16* UP, const u16* HALO, const float* sconv, const float* wconv, const float* bconv, float* out, int lane) {
;     ...
;     for (int tb = 0; tb < 64; tb += 16) {
;         unsigned gw[16], vw[16];
; #pragma unroll
;         for (int t = 0; t < 16; ++t) { const size_t row = (size_t)rb * 64 + tb + t; gw[t] = *(const unsigned*)(UP + row * FF2 + j0); vw[t] = *(const unsigned*)(UP + row * FF2 + FF + j0); }
; #pragma unroll
;         for (int t = 0; t < 16; ++t) {
;             const int row = rb * 64 + tb + t;
;             if (sample && (t & 3) == 0) { const int ns = (row - TP) >> 2; const float* s0 = sconv + (size_t)ns * 2 * FF2;
;                 const f32x2 a = *(const f32x2*)(s0 + j0), b = *(const f32x2*)(s0 + FF + j0), c = *(const f32x2*)(s0 + FF2 + j0), dd = *(const f32x2*)(s0 + FF2 + FF + j0);
;                 g2[0] = a.x; g2[1] = a.y; v2[0] = b.x; v2[1] = b.y; g1[0] = c.x; g1[1] = c.y; v1[0] = dd.x; v1[1] = dd.y; }
;             const float g0[2] = {bf2f(gw[t] & 0xffffu), bf2f(gw[t] >> 16)}, v0[2] = {bf2f(vw[t] & 0xffffu), bf2f(vw[t] >> 16)};
;             float res[2];
; #pragma unroll
;             for (int p = 0; p < 2; ++p) { const float cgv = bg[p] + wgt[0][p] * g2[p] + wgt[1][p] * g1[p] + wgt[2][p] * g0[p];
;                 const float cvv = bv[p] + wvl[0][p] * v2[p] + wvl[1][p] * v1[p] + wvl[2][p] * v0[p]; res[p] = gelu_t(cgv) * cvv;
;                 g2[p] = g1[p]; g1[p] = g0[p]; v2[p] = v1[p]; v1[p] = v0[p]; }
;             *(unsigned*)(UP + (size_t)row * FF2 + j0) = pk2(res[0], res[1]);
	v_lshlrev_b32_e32 v204, 16, v164
	v_and_b32_e32 v205, 0xffff0000, v164
	v_lshlrev_b32_e32 v206, 16, v165
	v_and_b32_e32 v207, 0xffff0000, v165
	v_pk_fma_f32 v[208:209], v[4:5], v[196:197], v[16:17]
	v_pk_fma_f32 v[210:211], v[6:7], v[198:199], v[18:19]
	v_pk_fma_f32 v[208:209], v[8:9], v[200:201], v[208:209]
	v_pk_fma_f32 v[210:211], v[10:11], v[202:203], v[210:211]
	v_pk_fma_f32 v[208:209], v[12:13], v[204:205], v[208:209]
	v_pk_fma_f32 v[210:211], v[14:15], v[206:207], v[210:211]
	v_pk_mul_f32 v[212:213], v[208:209], s[58:59]
	v_pk_mul_f32 v[212:213], v[208:209], v[212:213]
	v_pk_fma_f32 v[212:213], v[208:209], v[212:213], v[208:209]
	v_pk_mul_f32 v[212:213], v[212:213], s[60:61]
	v_pk_mul_f32 v[212:213], v[212:213], s[68:69]
	v_exp_f32_e32 v214, v212
	v_exp_f32_e32 v215, v213
	s_nop 0
	v_pk_add_f32 v[214:215], v[214:215], s[82:83]
	v_rcp_f32_e32 v214, v214
	v_rcp_f32_e32 v215, v215
	s_nop 0
	v_pk_mul_f32 v[212:213], v[208:209], v[214:215]
	v_pk_mul_f32 v[212:213], v[210:211], v[212:213]
	v_cvt_pk_bf16_f32 v216, v212, v213
	global_store_dword v2, v216, s[66:67]
	s_add_u32 s66, s66, 0x2c00
	s_addc_u32 s67, s67, 0
	s_waitcnt vmcnt(27)
	v_lshlrev_b32_e32 v196, 16, v166
	v_and_b32_e32 v197, 0xffff0000, v166
	v_lshlrev_b32_e32 v198, 16, v167
	v_and_b32_e32 v199, 0xffff0000, v167
	v_pk_fma_f32 v[208:209], v[4:5], v[200:201], v[16:17]
	v_pk_fma_f32 v[210:211], v[6:7], v[202:203], v[18:19]
	v_pk_fma_f32 v[208:209], v[8:9], v[204:205], v[208:209]
	v_pk_fma_f32 v[210:211], v[10:11], v[206:207], v[210:211]
	v_pk_fma_f32 v[208:209], v[12:13], v[196:197], v[208:209]
	v_pk_fma_f32 v[210:211], v[14:15], v[198:199], v[210:211]
	v_pk_mul_f32 v[212:213], v[208:209], s[58:59]
	v_pk_mul_f32 v[212:213], v[208:209], v[212:213]
	v_pk_fma_f32 v[212:213], v[208:209], v[212:213], v[208:209]
	v_pk_mul_f32 v[212:213], v[212:213], s[60:61]
	v_pk_mul_f32 v[212:213], v[212:213], s[68:69]
	v_exp_f32_e32 v214, v212
	v_exp_f32_e32 v215, v213
	s_nop 0
	v_pk_add_f32 v[214:215], v[214:215], s[82:83]
	v_rcp_f32_e32 v214, v214
	v_rcp_f32_e32 v215, v215
	s_nop 0
	v_pk_mul_f32 v[212:213], v[208:209], v[214:215]
	v_pk_mul_f32 v[212:213], v[210:211], v[212:213]
	v_cvt_pk_bf16_f32 v216, v212, v213
	global_store_dword v2, v216, s[66:67]
	s_add_u32 s66, s66, 0x2c00
	s_addc_u32 s67, s67, 0
	s_waitcnt vmcnt(26)
	v_lshlrev_b32_e32 v200, 16, v168
	v_and_b32_e32 v201, 0xffff0000, v168
	v_lshlrev_b32_e32 v202, 16, v169
	v_and_b32_e32 v203, 0xffff0000, v169
	v_pk_fma_f32 v[208:209], v[4:5], v[204:205], v[16:17]
	v_pk_fma_f32 v[210:211], v[6:7], v[206:207], v[18:19]
	v_pk_fma_f32 v[208:209], v[8:9], v[196:197], v[208:209]
	v_pk_fma_f32 v[210:211], v[10:11], v[198:199], v[210:211]
	v_pk_fma_f32 v[208:209], v[12:13], v[200:201], v[208:209]
	v_pk_fma_f32 v[210:211], v[14:15], v[202:203], v[210:211]
	v_pk_mul_f32 v[212:213], v[208:209], s[58:59]
	v_pk_mul_f32 v[212:213], v[208:209], v[212:213]
	v_pk_fma_f32 v[212:213], v[208:209], v[212:213], v[208:209]
	v_pk_mul_f32 v[212:213], v[212:213], s[60:61]
	v_pk_mul_f32 v[212:213], v[212:213], s[68:69]
	v_exp_f32_e32 v214, v212
	v_exp_f32_e32 v215, v213
	s_nop 0
	v_pk_add_f32 v[214:215], v[214:215], s[82:83]
	v_rcp_f32_e32 v214, v214
	v_rcp_f32_e32 v215, v215
	s_nop 0
	v_pk_mul_f32 v[212:213], v[208:209], v[214:215]
	v_pk_mul_f32 v[212:213], v[210:211], v[212:213]
	v_cvt_pk_bf16_f32 v216, v212, v213
	global_store_dword v2, v216, s[66:67]
	s_add_u32 s66, s66, 0x2c00
	s_addc_u32 s67, s67, 0
	s_waitcnt vmcnt(25)
	v_lshlrev_b32_e32 v204, 16, v170
	v_and_b32_e32 v205, 0xffff0000, v170
	v_lshlrev_b32_e32 v206, 16, v171
	v_and_b32_e32 v207, 0xffff0000, v171
	v_pk_fma_f32 v[208:209], v[4:5], v[196:197], v[16:17]
	v_pk_fma_f32 v[210:211], v[6:7], v[198:199], v[18:19]
	v_pk_fma_f32 v[208:209], v[8:9], v[200:201], v[208:209]
	v_pk_fma_f32 v[210:211], v[10:11], v[202:203], v[210:211]
	v_pk_fma_f32 v[208:209], v[12:13], v[204:205], v[208:209]
	v_pk_fma_f32 v[210:211], v[14:15], v[206:207], v[210:211]
	v_pk_mul_f32 v[212:213], v[208:209], s[58:59]
	v_pk_mul_f32 v[212:213], v[208:209], v[212:213]
	v_pk_fma_f32 v[212:213], v[208:209], v[212:213], v[208:209]
	v_pk_mul_f32 v[212:213], v[212:213], s[60:61]
	v_pk_mul_f32 v[212:213], v[212:213], s[68:69]
	v_exp_f32_e32 v214, v212
	v_exp_f32_e32 v215, v213
	s_nop 0
	v_pk_add_f32 v[214:215], v[214:215], s[82:83]
	v_rcp_f32_e32 v214, v214
	v_rcp_f32_e32 v215, v215
	s_nop 0
	v_pk_mul_f32 v[212:213], v[208:209], v[214:215]
	v_pk_mul_f32 v[212:213], v[210:211], v[212:213]
	v_cvt_pk_bf16_f32 v216, v212, v213
	global_store_dword v2, v216, s[66:67]
	s_add_u32 s66, s66, 0x2c00
	s_addc_u32 s67, s67, 0
	s_waitcnt vmcnt(24)
	v_lshlrev_b32_e32 v196, 16, v172
	v_and_b32_e32 v197, 0xffff0000, v172
	v_lshlrev_b32_e32 v198, 16, v173
	v_and_b32_e32 v199, 0xffff0000, v173
	v_pk_fma_f32 v[208:209], v[4:5], v[200:201], v[16:17]
	v_pk_fma_f32 v[210:211], v[6:7], v[202:203], v[18:19]
	v_pk_fma_f32 v[208:209], v[8:9], v[204:205], v[208:209]
	v_pk_fma_f32 v[210:211], v[10:11], v[206:207], v[210:211]
	v_pk_fma_f32 v[208:209], v[12:13], v[196:197], v[208:209]
	v_pk_fma_f32 v[210:211], v[14:15], v[198:199], v[210:211]
	v_pk_mul_f32 v[212:213], v[208:209], s[58:59]
	v_pk_mul_f32 v[212:213], v[208:209], v[212:213]
	v_pk_fma_f32 v[212:213], v[208:209], v[212:213], v[208:209]
	v_pk_mul_f32 v[212:213], v[212:213], s[60:61]
	v_pk_mul_f32 v[212:213], v[212:213], s[68:69]
	v_exp_f32_e32 v214, v212
	v_exp_f32_e32 v215, v213
	s_nop 0
	v_pk_add_f32 v[214:215], v[214:215], s[82:83]
	v_rcp_f32_e32 v214, v214
	v_rcp_f32_e32 v215, v215
	s_nop 0
	v_pk_mul_f32 v[212:213], v[208:209], v[214:215]
	v_pk_mul_f32 v[212:213], v[210:211], v[212:213]
	v_cvt_pk_bf16_f32 v216, v212, v213
	global_store_dword v2, v216, s[66:67]
	s_add_u32 s66, s66, 0x2c00
	s_addc_u32 s67, s67, 0
	s_waitcnt vmcnt(23)
; __device__ __forceinline__ float bf2f(unsigned b) { return __uint_as_float(b << 16); }
; __device__ __forceinline__ unsigned pk2(float lo, float hi) { unsigned r; asm("v_cvt_pk_bf16_f32 %0, %1, %2" : "=v"(r) : "v"(lo), "v"(hi)); return r; }
; __device__ __forceinline__ float gelu_t(float x) { return x * __builtin_amdgcn_rcpf(1.f + __expf(-1.5957691216057308f * (x + 0.044715f * x * x * x))); }
; __device__ __forceinline__ void act_item(int item, u16* UP, const u16* HALO, const float* sconv, const float* wconv, const float* bconv, float* out, int lane) {
;     ...
;     for (int tb = 0; tb < 64; tb += 16) {
;         unsigned gw[16], vw[16];
; #pragma unroll
;         for (int t = 0; t < 16; ++t) { const size_t row = (size_t)rb * 64 + tb + t; gw[t] = *(const unsigned*)(UP + row * FF2 + j0); vw[t] = *(const unsigned*)(UP + row * FF2 + FF + j0); }
; #pragma unroll
;         for (int t = 0; t < 16; ++t) {
;             const int row = rb * 64 + tb + t;
;             if (sample && (t & 3) == 0) { const int ns = (row - TP) >> 2; const float* s0 = sconv + (size_t)ns * 2 * FF2;
;                 const f32x2 a = *(const f32x2*)(s0 + j0), b = *(const f32x2*)(s0 + FF + j0), c = *(const f32x2*)(s0 + FF2 + j0), dd = *(const f32x2*)(s0 + FF2 + FF + j0);
;                 g2[0] = a.x; g2[1] = a.y; v2[0] = b.x; v2[1] = b.y; g1[0] = c.x; g1[1] = c.y; v1[0] = dd.x; v1[1] = dd.y; }
;             const float g0[2] = {bf2f(gw[t] & 0xffffu), bf2f(gw[t] >> 16)}, v0[2] = {bf2f(vw[t] & 0xffffu), bf2f(vw[t] >> 16)};
;             float res[2];
; #pragma unroll
;             for (int p = 0; p < 2; ++p) { const float cgv = bg[p] + wgt[0][p] * g2[p] + wgt[1][p] * g1[p] + wgt[2][p] * g0[p];
;                 const float cvv = bv[p] + wvl[0][p] * v2[p] + wvl[1][p] * v1[p] + wvl[2][p] * v0[p]; res[p] = gelu_t(cgv) * cvv;
;                 g2[p] = g1[p]; g1[p] = g0[p]; v2[p] = v1[p]; v1[p] = v0[p]; }
;             *(unsigned*)(UP + (size_t)row * FF2 + j0) = pk2(res[0], res[1]);
	v_lshlrev_b32_e32 v200, 16, v174
	v_and_b32_e32 v201, 0xffff0000, v174
	v_lshlrev_b32_e32 v202, 16, v175
	v_and_b32_e32 v203, 0xffff0000, v175
	v_pk_fma_f32 v[208:209], v[4:5], v[204:205], v[16:17]
	v_pk_fma_f32 v[210:211], v[6:7], v[206:207], v[18:19]
	v_pk_fma_f32 v[208:209], v[8:9], v[196:197], v[208:209]
	v_pk_fma_f32 v[210:211], v[10:11], v[198:199], v[210:211]
	v_pk_fma_f32 v[208:209], v[12:13], v[200:201], v[208:209]
	v_pk_fma_f32 v[210:211], v[14:15], v[202:203], v[210:211]
	v_pk_mul_f32 v[212:213], v[208:209], s[58:59]
	v_pk_mul_f32 v[212:213], v[208:209], v[212:213]
	v_pk_fma_f32 v[212:213], v[208:209], v[212:213], v[208:209]
	v_pk_mul_f32 v[212:213], v[212:213], s[60:61]
	v_pk_mul_f32 v[212:213], v[212:213], s[68:69]
	v_exp_f32_e32 v214, v212
	v_exp_f32_e32 v215, v213
	s_nop 0
	v_pk_add_f32 v[214:215], v[214:215], s[82:83]
	v_rcp_f32_e32 v214, v214
	v_rcp_f32_e32 v215, v215
	s_nop 0
	v_pk_mul_f32 v[212:213], v[208:209], v[214:215]
	v_pk_mul_f32 v[212:213], v[210:211], v[212:213]
	v_cvt_pk_bf16_f32 v216, v212, v213
	global_store_dword v2, v216, s[66:67]
	s_add_u32 s66, s66, 0x2c00
	s_addc_u32 s67, s67, 0
	s_waitcnt vmcnt(22)
	v_lshlrev_b32_e32 v204, 16, v176
	v_and_b32_e32 v205, 0xffff0000, v176
	v_lshlrev_b32_e32 v206, 16, v177
	v_and_b32_e32 v207, 0xffff0000, v177
	v_pk_fma_f32 v[208:209], v[4:5], v[196:197], v[16:17]
	v_pk_fma_f32 v[210:211], v[6:7], v[198:199], v[18:19]
	v_pk_fma_f32 v[208:209], v[8:9], v[200:201], v[208:209]
	v_pk_fma_f32 v[210:211], v[10:11], v[202:203], v[210:211]
	v_pk_fma_f32 v[208:209], v[12:13], v[204:205], v[208:209]
	v_pk_fma_f32 v[210:211], v[14:15], v[206:207], v[210:211]
	v_pk_mul_f32 v[212:213], v[208:209], s[58:59]
	v_pk_mul_f32 v[212:213], v[208:209], v[212:213]
	v_pk_fma_f32 v[212:213], v[208:209], v[212:213], v[208:209]
	v_pk_mul_f32 v[212:213], v[212:213], s[60:61]
	v_pk_mul_f32 v[212:213], v[212:213], s[68:69]
	v_exp_f32_e32 v214, v212
	v_exp_f32_e32 v215, v213
	s_nop 0
	v_pk_add_f32 v[214:215], v[214:215], s[82:83]
	v_rcp_f32_e32 v214, v214
	v_rcp_f32_e32 v215, v215
	s_nop 0
	v_pk_mul_f32 v[212:213], v[208:209], v[214:215]
	v_pk_mul_f32 v[212:213], v[210:211], v[212:213]
	v_cvt_pk_bf16_f32 v216, v212, v213
	global_store_dword v2, v216, s[66:67]
	s_add_u32 s66, s66, 0x2c00
	s_addc_u32 s67, s67, 0
	s_waitcnt vmcnt(21)
	v_lshlrev_b32_e32 v196, 16, v178
	v_and_b32_e32 v197, 0xffff0000, v178
	v_lshlrev_b32_e32 v198, 16, v179
	v_and_b32_e32 v199, 0xffff0000, v179
	v_pk_fma_f32 v[208:209], v[4:5], v[200:201], v[16:17]
	v_pk_fma_f32 v[210:211], v[6:7], v[202:203], v[18:19]
	v_pk_fma_f32 v[208:209], v[8:9], v[204:205], v[208:209]
	v_pk_fma_f32 v[210:211], v[10:11], v[206:207], v[210:211]
	v_pk_fma_f32 v[208:209], v[12:13], v[196:197], v[208:209]
	v_pk_fma_f32 v[210:211], v[14:15], v[198:199], v[210:211]
	v_pk_mul_f32 v[212:213], v[208:209], s[58:59]
	v_pk_mul_f32 v[212:213], v[208:209], v[212:213]
	v_pk_fma_f32 v[212:213], v[208:209], v[212:213], v[208:209]
	v_pk_mul_f32 v[212:213], v[212:213], s[60:61]
	v_pk_mul_f32 v[212:213], v[212:213], s[68:69]
	v_exp_f32_e32 v214, v212
	v_exp_f32_e32 v215, v213
	s_nop 0
	v_pk_add_f32 v[214:215], v[214:215], s[82:83]
	v_rcp_f32_e32 v214, v214
	v_rcp_f32_e32 v215, v215
	s_nop 0
	v_pk_mul_f32 v[212:213], v[208:209], v[214:215]
	v_pk_mul_f32 v[212:213], v[210:211], v[212:213]
	v_cvt_pk_bf16_f32 v216, v212, v213
	global_store_dword v2, v216, s[66:67]
	s_add_u32 s66, s66, 0x2c00
	s_addc_u32 s67, s67, 0
	s_waitcnt vmcnt(20)
	v_lshlrev_b32_e32 v200, 16, v180
	v_and_b32_e32 v201, 0xffff0000, v180
	v_lshlrev_b32_e32 v202, 16, v181
	v_and_b32_e32 v203, 0xffff0000, v181
	v_pk_fma_f32 v[208:209], v[4:5], v[204:205], v[16:17]
	v_pk_fma_f32 v[210:211], v[6:7], v[206:207], v[18:19]
	v_pk_fma_f32 v[208:209], v[8:9], v[196:197], v[208:209]
	v_pk_fma_f32 v[210:211], v[10:11], v[198:199], v[210:211]
	v_pk_fma_f32 v[208:209], v[12:13], v[200:201], v[208:209]
	v_pk_fma_f32 v[210:211], v[14:15], v[202:203], v[210:211]
	v_pk_mul_f32 v[212:213], v[208:209], s[58:59]
	v_pk_mul_f32 v[212:213], v[208:209], v[212:213]
	v_pk_fma_f32 v[212:213], v[208:209], v[212:213], v[208:209]
	v_pk_mul_f32 v[212:213], v[212:213], s[60:61]
	v_pk_mul_f32 v[212:213], v[212:213], s[68:69]
	v_exp_f32_e32 v214, v212
	v_exp_f32_e32 v215, v213
	s_nop 0
	v_pk_add_f32 v[214:215], v[214:215], s[82:83]
	v_rcp_f32_e32 v214, v214
	v_rcp_f32_e32 v215, v215
	s_nop 0
	v_pk_mul_f32 v[212:213], v[208:209], v[214:215]
	v_pk_mul_f32 v[212:213], v[210:211], v[212:213]
	v_cvt_pk_bf16_f32 v216, v212, v213
	global_store_dword v2, v216, s[66:67]
	s_add_u32 s66, s66, 0x2c00
	s_addc_u32 s67, s67, 0
	s_waitcnt vmcnt(19)
	v_lshlrev_b32_e32 v204, 16, v182
	v_and_b32_e32 v205, 0xffff0000, v182
	v_lshlrev_b32_e32 v206, 16, v183
	v_and_b32_e32 v207, 0xffff0000, v183
	v_pk_fma_f32 v[208:209], v[4:5], v[196:197], v[16:17]
	v_pk_fma_f32 v[210:211], v[6:7], v[198:199], v[18:19]
	v_pk_fma_f32 v[208:209], v[8:9], v[200:201], v[208:209]
	v_pk_fma_f32 v[210:211], v[10:11], v[202:203], v[210:211]
	v_pk_fma_f32 v[208:209], v[12:13], v[204:205], v[208:209]
	v_pk_fma_f32 v[210:211], v[14:15], v[206:207], v[210:211]
	v_pk_mul_f32 v[212:213], v[208:209], s[58:59]
	v_pk_mul_f32 v[212:213], v[208:209], v[212:213]
	v_pk_fma_f32 v[212:213], v[208:209], v[212:213], v[208:209]
	v_pk_mul_f32 v[212:213], v[212:213], s[60:61]
	v_pk_mul_f32 v[212:213], v[212:213], s[68:69]
	v_exp_f32_e32 v214, v212
	v_exp_f32_e32 v215, v213
	s_nop 0
	v_pk_add_f32 v[214:215], v[214:215], s[82:83]
	v_rcp_f32_e32 v214, v214
	v_rcp_f32_e32 v215, v215
	s_nop 0
	v_pk_mul_f32 v[212:213], v[208:209], v[214:215]
	v_pk_mul_f32 v[212:213], v[210:211], v[212:213]
	v_cvt_pk_bf16_f32 v216, v212, v213
	global_store_dword v2, v216, s[66:67]
	s_add_u32 s66, s66, 0x2c00
	s_addc_u32 s67, s67, 0
	s_waitcnt vmcnt(18)
; __device__ __forceinline__ float bf2f(unsigned b) { return __uint_as_float(b << 16); }
; __device__ __forceinline__ unsigned pk2(float lo, float hi) { unsigned r; asm("v_cvt_pk_bf16_f32 %0, %1, %2" : "=v"(r) : "v"(lo), "v"(hi)); return r; }
; __device__ __forceinline__ float gelu_t(float x) { return x * __builtin_amdgcn_rcpf(1.f + __expf(-1.5957691216057308f * (x + 0.044715f * x * x * x))); }
; __device__ __forceinline__ void act_item(int item, u16* UP, const u16* HALO, const float* sconv, const float* wconv, const float* bconv, float* out, int lane) {
;     ...
;     for (int tb = 0; tb < 64; tb += 16) {
;         unsigned gw[16], vw[16];
; #pragma unroll
;         for (int t = 0; t < 16; ++t) { const size_t row = (size_t)rb * 64 + tb + t; gw[t] = *(const unsigned*)(UP + row * FF2 + j0); vw[t] = *(const unsigned*)(UP + row * FF2 + FF + j0); }
; #pragma unroll
;         for (int t = 0; t < 16; ++t) {
;             const int row = rb * 64 + tb + t;
;             if (sample && (t & 3) == 0) { const int ns = (row - TP) >> 2; const float* s0 = sconv + (size_t)ns * 2 * FF2;
;                 const f32x2 a = *(const f32x2*)(s0 + j0), b = *(const f32x2*)(s0 + FF + j0), c = *(const f32x2*)(s0 + FF2 + j0), dd = *(const f32x2*)(s0 + FF2 + FF + j0);
;                 g2[0] = a.x; g2[1] = a.y; v2[0] = b.x; v2[1] = b.y; g1[0] = c.x; g1[1] = c.y; v1[0] = dd.x; v1[1] = dd.y; }
;             const float g0[2] = {bf2f(gw[t] & 0xffffu), bf2f(gw[t] >> 16)}, v0[2] = {bf2f(vw[t] & 0xffffu), bf2f(vw[t] >> 16)};
;             float res[2];
; #pragma unroll
;             for (int p = 0; p < 2; ++p) { const float cgv = bg[p] + wgt[0][p] * g2[p] + wgt[1][p] * g1[p] + wgt[2][p] * g0[p];
;                 const float cvv = bv[p] + wvl[0][p] * v2[p] + wvl[1][p] * v1[p] + wvl[2][p] * v0[p]; res[p] = gelu_t(cgv) * cvv;
;                 g2[p] = g1[p]; g1[p] = g0[p]; v2[p] = v1[p]; v1[p] = v0[p]; }
;             *(unsigned*)(UP + (size_t)row * FF2 + j0) = pk2(res[0], res[1]);
	v_lshlrev_b32_e32 v196, 16, v184
	v_and_b32_e32 v197, 0xffff0000, v184
	v_lshlrev_b32_e32 v198, 16, v185
	v_and_b32_e32 v199, 0xffff0000, v185
	v_pk_fma_f32 v[208:209], v[4:5], v[200:201], v[16:17]
	v_pk_fma_f32 v[210:211], v[6:7], v[202:203], v[18:19]
	v_pk_fma_f32 v[208:209], v[8:9], v[204:205], v[208:209]
	v_pk_fma_f32 v[210:211], v[10:11], v[206:207], v[210:211]
	v_pk_fma_f32 v[208:209], v[12:13], v[196:197], v[208:209]
	v_pk_fma_f32 v[210:211], v[14:15], v[198:199], v[210:211]
	v_pk_mul_f32 v[212:213], v[208:209], s[58:59]
	v_pk_mul_f32 v[212:213], v[208:209], v[212:213]
	v_pk_fma_f32 v[212:213], v[208:209], v[212:213], v[208:209]
	v_pk_mul_f32 v[212:213], v[212:213], s[60:61]
	v_pk_mul_f32 v[212:213], v[212:213], s[68:69]
	v_exp_f32_e32 v214, v212
	v_exp_f32_e32 v215, v213
	s_nop 0
	v_pk_add_f32 v[214:215], v[214:215], s[82:83]
	v_rcp_f32_e32 v214, v214
	v_rcp_f32_e32 v215, v215
	s_nop 0
	v_pk_mul_f32 v[212:213], v[208:209], v[214:215]
	v_pk_mul_f32 v[212:213], v[210:211], v[212:213]
	v_cvt_pk_bf16_f32 v216, v212, v213
	global_store_dword v2, v216, s[66:67]
	s_add_u32 s66, s66, 0x2c00
	s_addc_u32 s67, s67, 0
	s_waitcnt vmcnt(17)
	v_lshlrev_b32_e32 v200, 16, v186
	v_and_b32_e32 v201, 0xffff0000, v186
	v_lshlrev_b32_e32 v202, 16, v187
	v_and_b32_e32 v203, 0xffff0000, v187
	v_pk_fma_f32 v[208:209], v[4:5], v[204:205], v[16:17]
	v_pk_fma_f32 v[210:211], v[6:7], v[206:207], v[18:19]
	v_pk_fma_f32 v[208:209], v[8:9], v[196:197], v[208:209]
	v_pk_fma_f32 v[210:211], v[10:11], v[198:199], v[210:211]
	v_pk_fma_f32 v[208:209], v[12:13], v[200:201], v[208:209]
	v_pk_fma_f32 v[210:211], v[14:15], v[202:203], v[210:211]
	v_pk_mul_f32 v[212:213], v[208:209], s[58:59]
	v_pk_mul_f32 v[212:213], v[208:209], v[212:213]
	v_pk_fma_f32 v[212:213], v[208:209], v[212:213], v[208:209]
	v_pk_mul_f32 v[212:213], v[212:213], s[60:61]
	v_pk_mul_f32 v[212:213], v[212:213], s[68:69]
	v_exp_f32_e32 v214, v212
	v_exp_f32_e32 v215, v213
	s_nop 0
	v_pk_add_f32 v[214:215], v[214:215], s[82:83]
	v_rcp_f32_e32 v214, v214
	v_rcp_f32_e32 v215, v215
	s_nop 0
	v_pk_mul_f32 v[212:213], v[208:209], v[214:215]
	v_pk_mul_f32 v[212:213], v[210:211], v[212:213]
	v_cvt_pk_bf16_f32 v216, v212, v213
	global_store_dword v2, v216, s[66:67]
	s_add_u32 s66, s66, 0x2c00
	s_addc_u32 s67, s67, 0
	s_waitcnt vmcnt(16)
	v_lshlrev_b32_e32 v204, 16, v188
	v_and_b32_e32 v205, 0xffff0000, v188
	v_lshlrev_b32_e32 v206, 16, v189
	v_and_b32_e32 v207, 0xffff0000, v189
	v_pk_fma_f32 v[208:209], v[4:5], v[196:197], v[16:17]
	v_pk_fma_f32 v[210:211], v[6:7], v[198:199], v[18:19]
	v_pk_fma_f32 v[208:209], v[8:9], v[200:201], v[208:209]
	v_pk_fma_f32 v[210:211], v[10:11], v[202:203], v[210:211]
	v_pk_fma_f32 v[208:209], v[12:13], v[204:205], v[208:209]
	v_pk_fma_f32 v[210:211], v[14:15], v[206:207], v[210:211]
	v_pk_mul_f32 v[212:213], v[208:209], s[58:59]
	v_pk_mul_f32 v[212:213], v[208:209], v[212:213]
	v_pk_fma_f32 v[212:213], v[208:209], v[212:213], v[208:209]
	v_pk_mul_f32 v[212:213], v[212:213], s[60:61]
	v_pk_mul_f32 v[212:213], v[212:213], s[68:69]
	v_exp_f32_e32 v214, v212
	v_exp_f32_e32 v215, v213
	s_nop 0
	v_pk_add_f32 v[214:215], v[214:215], s[82:83]
	v_rcp_f32_e32 v214, v214
	v_rcp_f32_e32 v215, v215
	s_nop 0
	v_pk_mul_f32 v[212:213], v[208:209], v[214:215]
	v_pk_mul_f32 v[212:213], v[210:211], v[212:213]
	v_cvt_pk_bf16_f32 v216, v212, v213
	global_store_dword v2, v216, s[66:67]
	s_add_u32 s66, s66, 0x2c00
	s_addc_u32 s67, s67, 0
	s_waitcnt vmcnt(15)
	v_lshlrev_b32_e32 v196, 16, v190
	v_and_b32_e32 v197, 0xffff0000, v190
	v_lshlrev_b32_e32 v198, 16, v191
	v_and_b32_e32 v199, 0xffff0000, v191
	v_pk_fma_f32 v[208:209], v[4:5], v[200:201], v[16:17]
	v_pk_fma_f32 v[210:211], v[6:7], v[202:203], v[18:19]
	v_pk_fma_f32 v[208:209], v[8:9], v[204:205], v[208:209]
	v_pk_fma_f32 v[210:211], v[10:11], v[206:207], v[210:211]
	v_pk_fma_f32 v[208:209], v[12:13], v[196:197], v[208:209]
	v_pk_fma_f32 v[210:211], v[14:15], v[198:199], v[210:211]
	v_pk_mul_f32 v[212:213], v[208:209], s[58:59]
	v_pk_mul_f32 v[212:213], v[208:209], v[212:213]
	v_pk_fma_f32 v[212:213], v[208:209], v[212:213], v[208:209]
	v_pk_mul_f32 v[212:213], v[212:213], s[60:61]
	v_pk_mul_f32 v[212:213], v[212:213], s[68:69]
	v_exp_f32_e32 v214, v212
	v_exp_f32_e32 v215, v213
	s_nop 0
	v_pk_add_f32 v[214:215], v[214:215], s[82:83]
	v_rcp_f32_e32 v214, v214
	v_rcp_f32_e32 v215, v215
	s_nop 0
	v_pk_mul_f32 v[212:213], v[208:209], v[214:215]
	v_pk_mul_f32 v[212:213], v[210:211], v[212:213]
	v_cvt_pk_bf16_f32 v216, v212, v213
	global_store_dword v2, v216, s[66:67]
	s_add_u32 s66, s66, 0x2c00
	s_addc_u32 s67, s67, 0
	global_load_dword v160, v2, s[64:65]
	global_load_dword v161, v3, s[64:65]
	s_add_u32 s64, s64, 0x2c00
	s_addc_u32 s65, s65, 0
	global_load_dword v162, v2, s[64:65]
	global_load_dword v163, v3, s[64:65]
	s_add_u32 s64, s64, 0x2c00
	s_addc_u32 s65, s65, 0
	global_load_dword v164, v2, s[64:65]
	global_load_dword v165, v3, s[64:65]
	s_add_u32 s64, s64, 0x2c00
	s_addc_u32 s65, s65, 0
	global_load_dword v166, v2, s[64:65]
	global_load_dword v167, v3, s[64:65]
	s_add_u32 s64, s64, 0x2c00
	s_addc_u32 s65, s65, 0
	global_load_dword v168, v2, s[64:65]
	global_load_dword v169, v3, s[64:65]
	s_add_u32 s64, s64, 0x2c00
	s_addc_u32 s65, s65, 0
	global_load_dword v170, v2, s[64:65]
	global_load_dword v171, v3, s[64:65]
	s_add_u32 s64, s64, 0x2c00
	s_addc_u32 s65, s65, 0
	global_load_dword v172, v2, s[64:65]
	global_load_dword v173, v3, s[64:65]
	s_add_u32 s64, s64, 0x2c00
	s_addc_u32 s65, s65, 0
	global_load_dword v174, v2, s[64:65]
	global_load_dword v175, v3, s[64:65]
	s_add_u32 s64, s64, 0x2c00
	s_addc_u32 s65, s65, 0
	global_load_dword v176, v2, s[64:65]
	global_load_dword v177, v3, s[64:65]
	s_add_u32 s64, s64, 0x2c00
	s_addc_u32 s65, s65, 0
	global_load_dword v178, v2, s[64:65]
	global_load_dword v179, v3, s[64:65]
	s_add_u32 s64, s64, 0x2c00
	s_addc_u32 s65, s65, 0
	global_load_dword v180, v2, s[64:65]
	global_load_dword v181, v3, s[64:65]
	s_add_u32 s64, s64, 0x2c00
	s_addc_u32 s65, s65, 0
	global_load_dword v182, v2, s[64:65]
	global_load_dword v183, v3, s[64:65]
	s_add_u32 s64, s64, 0x2c00
	s_addc_u32 s65, s65, 0
	global_load_dword v184, v2, s[64:65]
	global_load_dword v185, v3, s[64:65]
	s_add_u32 s64, s64, 0x2c00
	s_addc_u32 s65, s65, 0
	global_load_dword v186, v2, s[64:65]
	global_load_dword v187, v3, s[64:65]
	s_add_u32 s64, s64, 0x2c00
	s_addc_u32 s65, s65, 0
	global_load_dword v188, v2, s[64:65]
	global_load_dword v189, v3, s[64:65]
	s_add_u32 s64, s64, 0x2c00
	s_addc_u32 s65, s65, 0
	global_load_dword v190, v2, s[64:65]
	global_load_dword v191, v3, s[64:65]
	s_add_u32 s64, s64, 0x2c00
	s_addc_u32 s65, s65, 0
	s_waitcnt vmcnt(30)
; __device__ __forceinline__ float bf2f(unsigned b) { return __uint_as_float(b << 16); }
; __device__ __forceinline__ unsigned pk2(float lo, float hi) { unsigned r; asm("v_cvt_pk_bf16_f32 %0, %1, %2" : "=v"(r) : "v"(lo), "v"(hi)); return r; }
; __device__ __forceinline__ float gelu_t(float x) { return x * __builtin_amdgcn_rcpf(1.f + __expf(-1.5957691216057308f * (x + 0.044715f * x * x * x))); }
; __device__ __forceinline__ void act_item(int item, u16* UP, const u16* HALO, const float* sconv, const float* wconv, const float* bconv, float* out, int lane) {
;     ...
;     for (int tb = 0; tb < 64; tb += 16) {
;         unsigned gw[16], vw[16];
; #pragma unroll
;         for (int t = 0; t < 16; ++t) { const size_t row = (size_t)rb * 64 + tb + t; gw[t] = *(const unsigned*)(UP + row * FF2 + j0); vw[t] = *(const unsigned*)(UP + row * FF2 + FF + j0); }
; #pragma unroll
;         for (int t = 0; t < 16; ++t) {
;             const int row = rb * 64 + tb + t;
;             if (sample && (t & 3) == 0) { const int ns = (row - TP) >> 2; const float* s0 = sconv + (size_t)ns * 2 * FF2;
;                 const f32x2 a = *(const f32x2*)(s0 + j0), b = *(const f32x2*)(s0 + FF + j0), c = *(const f32x2*)(s0 + FF2 + j0), dd = *(const f32x2*)(s0 + FF2 + FF + j0);
;                 g2[0] = a.x; g2[1] = a.y; v2[0] = b.x; v2[1] = b.y; g1[0] = c.x; g1[1] = c.y; v1[0] = dd.x; v1[1] = dd.y; }
;             const float g0[2] = {bf2f(gw[t] & 0xffffu), bf2f(gw[t] >> 16)}, v0[2] = {bf2f(vw[t] & 0xffffu), bf2f(vw[t] >> 16)};
;             float res[2];
; #pragma unroll
;             for (int p = 0; p < 2; ++p) { const float cgv = bg[p] + wgt[0][p] * g2[p] + wgt[1][p] * g1[p] + wgt[2][p] * g0[p];
;                 const float cvv = bv[p] + wvl[0][p] * v2[p] + wvl[1][p] * v1[p] + wvl[2][p] * v0[p]; res[p] = gelu_t(cgv) * cvv;
;                 g2[p] = g1[p]; g1[p] = g0[p]; v2[p] = v1[p]; v1[p] = v0[p]; }
;             *(unsigned*)(UP + (size_t)row * FF2 + j0) = pk2(res[0], res[1]);
	v_lshlrev_b32_e32 v200, 16, v160
	v_and_b32_e32 v201, 0xffff0000, v160
	v_lshlrev_b32_e32 v202, 16, v161
	v_and_b32_e32 v203, 0xffff0000, v161
	v_pk_fma_f32 v[208:209], v[4:5], v[204:205], v[16:17]
	v_pk_fma_f32 v[210:211], v[6:7], v[206:207], v[18:19]
	v_pk_fma_f32 v[208:209], v[8:9], v[196:197], v[208:209]
	v_pk_fma_f32 v[210:211], v[10:11], v[198:199], v[210:211]
	v_pk_fma_f32 v[208:209], v[12:13], v[200:201], v[208:209]
	v_pk_fma_f32 v[210:211], v[14:15], v[202:203], v[210:211]
	v_pk_mul_f32 v[212:213], v[208:209], s[58:59]
	v_pk_mul_f32 v[212:213], v[208:209], v[212:213]
	v_pk_fma_f32 v[212:213], v[208:209], v[212:213], v[208:209]
	v_pk_mul_f32 v[212:213], v[212:213], s[60:61]
	v_pk_mul_f32 v[212:213], v[212:213], s[68:69]
	v_exp_f32_e32 v214, v212
	v_exp_f32_e32 v215, v213
	s_nop 0
	v_pk_add_f32 v[214:215], v[214:215], s[82:83]
	v_rcp_f32_e32 v214, v214
	v_rcp_f32_e32 v215, v215
	s_nop 0
	v_pk_mul_f32 v[212:213], v[208:209], v[214:215]
	v_pk_mul_f32 v[212:213], v[210:211], v[212:213]
	v_cvt_pk_bf16_f32 v216, v212, v213
	global_store_dword v2, v216, s[66:67]
	s_add_u32 s66, s66, 0x2c00
	s_addc_u32 s67, s67, 0
	s_waitcnt vmcnt(29)
	v_lshlrev_b32_e32 v204, 16, v162
	v_and_b32_e32 v205, 0xffff0000, v162
	v_lshlrev_b32_e32 v206, 16, v163
	v_and_b32_e32 v207, 0xffff0000, v163
	v_pk_fma_f32 v[208:209], v[4:5], v[196:197], v[16:17]
	v_pk_fma_f32 v[210:211], v[6:7], v[198:199], v[18:19]
	v_pk_fma_f32 v[208:209], v[8:9], v[200:201], v[208:209]
	v_pk_fma_f32 v[210:211], v[10:11], v[202:203], v[210:211]
	v_pk_fma_f32 v[208:209], v[12:13], v[204:205], v[208:209]
	v_pk_fma_f32 v[210:211], v[14:15], v[206:207], v[210:211]
	v_pk_mul_f32 v[212:213], v[208:209], s[58:59]
	v_pk_mul_f32 v[212:213], v[208:209], v[212:213]
	v_pk_fma_f32 v[212:213], v[208:209], v[212:213], v[208:209]
	v_pk_mul_f32 v[212:213], v[212:213], s[60:61]
	v_pk_mul_f32 v[212:213], v[212:213], s[68:69]
	v_exp_f32_e32 v214, v212
	v_exp_f32_e32 v215, v213
	s_nop 0
	v_pk_add_f32 v[214:215], v[214:215], s[82:83]
	v_rcp_f32_e32 v214, v214
	v_rcp_f32_e32 v215, v215
	s_nop 0
	v_pk_mul_f32 v[212:213], v[208:209], v[214:215]
	v_pk_mul_f32 v[212:213], v[210:211], v[212:213]
	v_cvt_pk_bf16_f32 v216, v212, v213
	global_store_dword v2, v216, s[66:67]
	s_add_u32 s66, s66, 0x2c00
	s_addc_u32 s67, s67, 0
	s_waitcnt vmcnt(28)
	v_lshlrev_b32_e32 v196, 16, v164
	v_and_b32_e32 v197, 0xffff0000, v164
	v_lshlrev_b32_e32 v198, 16, v165
	v_and_b32_e32 v199, 0xffff0000, v165
	v_pk_fma_f32 v[208:209], v[4:5], v[200:201], v[16:17]
	v_pk_fma_f32 v[210:211], v[6:7], v[202:203], v[18:19]
	v_pk_fma_f32 v[208:209], v[8:9], v[204:205], v[208:209]
	v_pk_fma_f32 v[210:211], v[10:11], v[206:207], v[210:211]
	v_pk_fma_f32 v[208:209], v[12:13], v[196:197], v[208:209]
	v_pk_fma_f32 v[210:211], v[14:15], v[198:199], v[210:211]
	v_pk_mul_f32 v[212:213], v[208:209], s[58:59]
	v_pk_mul_f32 v[212:213], v[208:209], v[212:213]
	v_pk_fma_f32 v[212:213], v[208:209], v[212:213], v[208:209]
	v_pk_mul_f32 v[212:213], v[212:213], s[60:61]
	v_pk_mul_f32 v[212:213], v[212:213], s[68:69]
	v_exp_f32_e32 v214, v212
	v_exp_f32_e32 v215, v213
	s_nop 0
	v_pk_add_f32 v[214:215], v[214:215], s[82:83]
	v_rcp_f32_e32 v214, v214
	v_rcp_f32_e32 v215, v215
	s_nop 0
	v_pk_mul_f32 v[212:213], v[208:209], v[214:215]
	v_pk_mul_f32 v[212:213], v[210:211], v[212:213]
	v_cvt_pk_bf16_f32 v216, v212, v213
	global_store_dword v2, v216, s[66:67]
	s_add_u32 s66, s66, 0x2c00
	s_addc_u32 s67, s67, 0
	s_waitcnt vmcnt(27)
	v_lshlrev_b32_e32 v200, 16, v166
	v_and_b32_e32 v201, 0xffff0000, v166
	v_lshlrev_b32_e32 v202, 16, v167
	v_and_b32_e32 v203, 0xffff0000, v167
	v_pk_fma_f32 v[208:209], v[4:5], v[204:205], v[16:17]
	v_pk_fma_f32 v[210:211], v[6:7], v[206:207], v[18:19]
	v_pk_fma_f32 v[208:209], v[8:9], v[196:197], v[208:209]
	v_pk_fma_f32 v[210:211], v[10:11], v[198:199], v[210:211]
	v_pk_fma_f32 v[208:209], v[12:13], v[200:201], v[208:209]
	v_pk_fma_f32 v[210:211], v[14:15], v[202:203], v[210:211]
	v_pk_mul_f32 v[212:213], v[208:209], s[58:59]
	v_pk_mul_f32 v[212:213], v[208:209], v[212:213]
	v_pk_fma_f32 v[212:213], v[208:209], v[212:213], v[208:209]
	v_pk_mul_f32 v[212:213], v[212:213], s[60:61]
	v_pk_mul_f32 v[212:213], v[212:213], s[68:69]
	v_exp_f32_e32 v214, v212
	v_exp_f32_e32 v215, v213
	s_nop 0
	v_pk_add_f32 v[214:215], v[214:215], s[82:83]
	v_rcp_f32_e32 v214, v214
	v_rcp_f32_e32 v215, v215
	s_nop 0
	v_pk_mul_f32 v[212:213], v[208:209], v[214:215]
	v_pk_mul_f32 v[212:213], v[210:211], v[212:213]
	v_cvt_pk_bf16_f32 v216, v212, v213
	global_store_dword v2, v216, s[66:67]
	s_add_u32 s66, s66, 0x2c00
	s_addc_u32 s67, s67, 0
	s_waitcnt vmcnt(26)
	v_lshlrev_b32_e32 v204, 16, v168
	v_and_b32_e32 v205, 0xffff0000, v168
	v_lshlrev_b32_e32 v206, 16, v169
	v_and_b32_e32 v207, 0xffff0000, v169
	v_pk_fma_f32 v[208:209], v[4:5], v[196:197], v[16:17]
	v_pk_fma_f32 v[210:211], v[6:7], v[198:199], v[18:19]
	v_pk_fma_f32 v[208:209], v[8:9], v[200:201], v[208:209]
	v_pk_fma_f32 v[210:211], v[10:11], v[202:203], v[210:211]
	v_pk_fma_f32 v[208:209], v[12:13], v[204:205], v[208:209]
	v_pk_fma_f32 v[210:211], v[14:15], v[206:207], v[210:211]
	v_pk_mul_f32 v[212:213], v[208:209], s[58:59]
	v_pk_mul_f32 v[212:213], v[208:209], v[212:213]
	v_pk_fma_f32 v[212:213], v[208:209], v[212:213], v[208:209]
	v_pk_mul_f32 v[212:213], v[212:213], s[60:61]
	v_pk_mul_f32 v[212:213], v[212:213], s[68:69]
	v_exp_f32_e32 v214, v212
	v_exp_f32_e32 v215, v213
	s_nop 0
	v_pk_add_f32 v[214:215], v[214:215], s[82:83]
	v_rcp_f32_e32 v214, v214
	v_rcp_f32_e32 v215, v215
	s_nop 0
	v_pk_mul_f32 v[212:213], v[208:209], v[214:215]
	v_pk_mul_f32 v[212:213], v[210:211], v[212:213]
	v_cvt_pk_bf16_f32 v216, v212, v213
	global_store_dword v2, v216, s[66:67]
	s_add_u32 s66, s66, 0x2c00
	s_addc_u32 s67, s67, 0
	s_waitcnt vmcnt(25)
; __device__ __forceinline__ float bf2f(unsigned b) { return __uint_as_float(b << 16); }
; __device__ __forceinline__ unsigned pk2(float lo, float hi) { unsigned r; asm("v_cvt_pk_bf16_f32 %0, %1, %2" : "=v"(r) : "v"(lo), "v"(hi)); return r; }
; __device__ __forceinline__ float gelu_t(float x) { return x * __builtin_amdgcn_rcpf(1.f + __expf(-1.5957691216057308f * (x + 0.044715f * x * x * x))); }
; __device__ __forceinline__ void act_item(int item, u16* UP, const u16* HALO, const float* sconv, const float* wconv, const float* bconv, float* out, int lane) {
;     ...
;     for (int tb = 0; tb < 64; tb += 16) {
;         unsigned gw[16], vw[16];
; #pragma unroll
;         for (int t = 0; t < 16; ++t) { const size_t row = (size_t)rb * 64 + tb + t; gw[t] = *(const unsigned*)(UP + row * FF2 + j0); vw[t] = *(const unsigned*)(UP + row * FF2 + FF + j0); }
; #pragma unroll
;         for (int t = 0; t < 16; ++t) {
;             const int row = rb * 64 + tb + t;
;             if (sample && (t & 3) == 0) { const int ns = (row - TP) >> 2; const float* s0 = sconv + (size_t)ns * 2 * FF2;
;                 const f32x2 a = *(const f32x2*)(s0 + j0), b = *(const f32x2*)(s0 + FF + j0), c = *(const f32x2*)(s0 + FF2 + j0), dd = *(const f32x2*)(s0 + FF2 + FF + j0);
;                 g2[0] = a.x; g2[1] = a.y; v2[0] = b.x; v2[1] = b.y; g1[0] = c.x; g1[1] = c.y; v1[0] = dd.x; v1[1] = dd.y; }
;             const float g0[2] = {bf2f(gw[t] & 0xffffu), bf2f(gw[t] >> 16)}, v0[2] = {bf2f(vw[t] & 0xffffu), bf2f(vw[t] >> 16)};
;             float res[2];
; #pragma unroll
;             for (int p = 0; p < 2; ++p) { const float cgv = bg[p] + wgt[0][p] * g2[p] + wgt[1][p] * g1[p] + wgt[2][p] * g0[p];
;                 const float cvv = bv[p] + wvl[0][p] * v2[p] + wvl[1][p] * v1[p] + wvl[2][p] * v0[p]; res[p] = gelu_t(cgv) * cvv;
;                 g2[p] = g1[p]; g1[p] = g0[p]; v2[p] = v1[p]; v1[p] = v0[p]; }
;             *(unsigned*)(UP + (size_t)row * FF2 + j0) = pk2(res[0], res[1]);
	v_lshlrev_b32_e32 v196, 16, v170
	v_and_b32_e32 v197, 0xffff0000, v170
	v_lshlrev_b32_e32 v198, 16, v171
	v_and_b32_e32 v199, 0xffff0000, v171
	v_pk_fma_f32 v[208:209], v[4:5], v[200:201], v[16:17]
	v_pk_fma_f32 v[210:211], v[6:7], v[202:203], v[18:19]
	v_pk_fma_f32 v[208:209], v[8:9], v[204:205], v[208:209]
	v_pk_fma_f32 v[210:211], v[10:11], v[206:207], v[210:211]
	v_pk_fma_f32 v[208:209], v[12:13], v[196:197], v[208:209]
	v_pk_fma_f32 v[210:211], v[14:15], v[198:199], v[210:211]
	v_pk_mul_f32 v[212:213], v[208:209], s[58:59]
	v_pk_mul_f32 v[212:213], v[208:209], v[212:213]
	v_pk_fma_f32 v[212:213], v[208:209], v[212:213], v[208:209]
	v_pk_mul_f32 v[212:213], v[212:213], s[60:61]
	v_pk_mul_f32 v[212:213], v[212:213], s[68:69]
	v_exp_f32_e32 v214, v212
	v_exp_f32_e32 v215, v213
	s_nop 0
	v_pk_add_f32 v[214:215], v[214:215], s[82:83]
	v_rcp_f32_e32 v214, v214
	v_rcp_f32_e32 v215, v215
	s_nop 0
	v_pk_mul_f32 v[212:213], v[208:209], v[214:215]
	v_pk_mul_f32 v[212:213], v[210:211], v[212:213]
	v_cvt_pk_bf16_f32 v216, v212, v213
	global_store_dword v2, v216, s[66:67]
	s_add_u32 s66, s66, 0x2c00
	s_addc_u32 s67, s67, 0
	s_waitcnt vmcnt(24)
	v_lshlrev_b32_e32 v200, 16, v172
	v_and_b32_e32 v201, 0xffff0000, v172
	v_lshlrev_b32_e32 v202, 16, v173
	v_and_b32_e32 v203, 0xffff0000, v173
	v_pk_fma_f32 v[208:209], v[4:5], v[204:205], v[16:17]
	v_pk_fma_f32 v[210:211], v[6:7], v[206:207], v[18:19]
	v_pk_fma_f32 v[208:209], v[8:9], v[196:197], v[208:209]
	v_pk_fma_f32 v[210:211], v[10:11], v[198:199], v[210:211]
	v_pk_fma_f32 v[208:209], v[12:13], v[200:201], v[208:209]
	v_pk_fma_f32 v[210:211], v[14:15], v[202:203], v[210:211]
	v_pk_mul_f32 v[212:213], v[208:209], s[58:59]
	v_pk_mul_f32 v[212:213], v[208:209], v[212:213]
	v_pk_fma_f32 v[212:213], v[208:209], v[212:213], v[208:209]
	v_pk_mul_f32 v[212:213], v[212:213], s[60:61]
	v_pk_mul_f32 v[212:213], v[212:213], s[68:69]
	v_exp_f32_e32 v214, v212
	v_exp_f32_e32 v215, v213
	s_nop 0
	v_pk_add_f32 v[214:215], v[214:215], s[82:83]
	v_rcp_f32_e32 v214, v214
	v_rcp_f32_e32 v215, v215
	s_nop 0
	v_pk_mul_f32 v[212:213], v[208:209], v[214:215]
	v_pk_mul_f32 v[212:213], v[210:211], v[212:213]
	v_cvt_pk_bf16_f32 v216, v212, v213
	global_store_dword v2, v216, s[66:67]
	s_add_u32 s66, s66, 0x2c00
	s_addc_u32 s67, s67, 0
	s_waitcnt vmcnt(23)
	v_lshlrev_b32_e32 v204, 16, v174
	v_and_b32_e32 v205, 0xffff0000, v174
	v_lshlrev_b32_e32 v206, 16, v175
	v_and_b32_e32 v207, 0xffff0000, v175
	v_pk_fma_f32 v[208:209], v[4:5], v[196:197], v[16:17]
	v_pk_fma_f32 v[210:211], v[6:7], v[198:199], v[18:19]
	v_pk_fma_f32 v[208:209], v[8:9], v[200:201], v[208:209]
	v_pk_fma_f32 v[210:211], v[10:11], v[202:203], v[210:211]
	v_pk_fma_f32 v[208:209], v[12:13], v[204:205], v[208:209]
	v_pk_fma_f32 v[210:211], v[14:15], v[206:207], v[210:211]
	v_pk_mul_f32 v[212:213], v[208:209], s[58:59]
	v_pk_mul_f32 v[212:213], v[208:209], v[212:213]
	v_pk_fma_f32 v[212:213], v[208:209], v[212:213], v[208:209]
	v_pk_mul_f32 v[212:213], v[212:213], s[60:61]
	v_pk_mul_f32 v[212:213], v[212:213], s[68:69]
	v_exp_f32_e32 v214, v212
	v_exp_f32_e32 v215, v213
	s_nop 0
	v_pk_add_f32 v[214:215], v[214:215], s[82:83]
	v_rcp_f32_e32 v214, v214
	v_rcp_f32_e32 v215, v215
	s_nop 0
	v_pk_mul_f32 v[212:213], v[208:209], v[214:215]
	v_pk_mul_f32 v[212:213], v[210:211], v[212:213]
	v_cvt_pk_bf16_f32 v216, v212, v213
	global_store_dword v2, v216, s[66:67]
	s_add_u32 s66, s66, 0x2c00
	s_addc_u32 s67, s67, 0
	s_waitcnt vmcnt(22)
	v_lshlrev_b32_e32 v196, 16, v176
	v_and_b32_e32 v197, 0xffff0000, v176
	v_lshlrev_b32_e32 v198, 16, v177
	v_and_b32_e32 v199, 0xffff0000, v177
	v_pk_fma_f32 v[208:209], v[4:5], v[200:201], v[16:17]
	v_pk_fma_f32 v[210:211], v[6:7], v[202:203], v[18:19]
	v_pk_fma_f32 v[208:209], v[8:9], v[204:205], v[208:209]
	v_pk_fma_f32 v[210:211], v[10:11], v[206:207], v[210:211]
	v_pk_fma_f32 v[208:209], v[12:13], v[196:197], v[208:209]
	v_pk_fma_f32 v[210:211], v[14:15], v[198:199], v[210:211]
	v_pk_mul_f32 v[212:213], v[208:209], s[58:59]
	v_pk_mul_f32 v[212:213], v[208:209], v[212:213]
	v_pk_fma_f32 v[212:213], v[208:209], v[212:213], v[208:209]
	v_pk_mul_f32 v[212:213], v[212:213], s[60:61]
	v_pk_mul_f32 v[212:213], v[212:213], s[68:69]
	v_exp_f32_e32 v214, v212
	v_exp_f32_e32 v215, v213
	s_nop 0
	v_pk_add_f32 v[214:215], v[214:215], s[82:83]
	v_rcp_f32_e32 v214, v214
	v_rcp_f32_e32 v215, v215
	s_nop 0
	v_pk_mul_f32 v[212:213], v[208:209], v[214:215]
	v_pk_mul_f32 v[212:213], v[210:211], v[212:213]
	v_cvt_pk_bf16_f32 v216, v212, v213
	global_store_dword v2, v216, s[66:67]
	s_add_u32 s66, s66, 0x2c00
	s_addc_u32 s67, s67, 0
	s_waitcnt vmcnt(21)
	v_lshlrev_b32_e32 v200, 16, v178
	v_and_b32_e32 v201, 0xffff0000, v178
	v_lshlrev_b32_e32 v202, 16, v179
	v_and_b32_e32 v203, 0xffff0000, v179
	v_pk_fma_f32 v[208:209], v[4:5], v[204:205], v[16:17]
	v_pk_fma_f32 v[210:211], v[6:7], v[206:207], v[18:19]
	v_pk_fma_f32 v[208:209], v[8:9], v[196:197], v[208:209]
	v_pk_fma_f32 v[210:211], v[10:11], v[198:199], v[210:211]
	v_pk_fma_f32 v[208:209], v[12:13], v[200:201], v[208:209]
	v_pk_fma_f32 v[210:211], v[14:15], v[202:203], v[210:211]
	v_pk_mul_f32 v[212:213], v[208:209], s[58:59]
	v_pk_mul_f32 v[212:213], v[208:209], v[212:213]
	v_pk_fma_f32 v[212:213], v[208:209], v[212:213], v[208:209]
	v_pk_mul_f32 v[212:213], v[212:213], s[60:61]
	v_pk_mul_f32 v[212:213], v[212:213], s[68:69]
	v_exp_f32_e32 v214, v212
	v_exp_f32_e32 v215, v213
	s_nop 0
	v_pk_add_f32 v[214:215], v[214:215], s[82:83]
	v_rcp_f32_e32 v214, v214
	v_rcp_f32_e32 v215, v215
	s_nop 0
	v_pk_mul_f32 v[212:213], v[208:209], v[214:215]
	v_pk_mul_f32 v[212:213], v[210:211], v[212:213]
	v_cvt_pk_bf16_f32 v216, v212, v213
	global_store_dword v2, v216, s[66:67]
	s_add_u32 s66, s66, 0x2c00
	s_addc_u32 s67, s67, 0
	s_waitcnt vmcnt(20)
; __device__ __forceinline__ float bf2f(unsigned b) { return __uint_as_float(b << 16); }
; __device__ __forceinline__ unsigned pk2(float lo, float hi) { unsigned r; asm("v_cvt_pk_bf16_f32 %0, %1, %2" : "=v"(r) : "v"(lo), "v"(hi)); return r; }
; __device__ __forceinline__ float gelu_t(float x) { return x * __builtin_amdgcn_rcpf(1.f + __expf(-1.5957691216057308f * (x + 0.044715f * x * x * x))); }
; __device__ __forceinline__ void act_item(int item, u16* UP, const u16* HALO, const float* sconv, const float* wconv, const float* bconv, float* out, int lane) {
;     ...
;     for (int tb = 0; tb < 64; tb += 16) {
;         unsigned gw[16], vw[16];
; #pragma unroll
;         for (int t = 0; t < 16; ++t) { const size_t row = (size_t)rb * 64 + tb + t; gw[t] = *(const unsigned*)(UP + row * FF2 + j0); vw[t] = *(const unsigned*)(UP + row * FF2 + FF + j0); }
; #pragma unroll
;         for (int t = 0; t < 16; ++t) {
;             const int row = rb * 64 + tb + t;
;             if (sample && (t & 3) == 0) { const int ns = (row - TP) >> 2; const float* s0 = sconv + (size_t)ns * 2 * FF2;
;                 const f32x2 a = *(const f32x2*)(s0 + j0), b = *(const f32x2*)(s0 + FF + j0), c = *(const f32x2*)(s0 + FF2 + j0), dd = *(const f32x2*)(s0 + FF2 + FF + j0);
;                 g2[0] = a.x; g2[1] = a.y; v2[0] = b.x; v2[1] = b.y; g1[0] = c.x; g1[1] = c.y; v1[0] = dd.x; v1[1] = dd.y; }
;             const float g0[2] = {bf2f(gw[t] & 0xffffu), bf2f(gw[t] >> 16)}, v0[2] = {bf2f(vw[t] & 0xffffu), bf2f(vw[t] >> 16)};
;             float res[2];
; #pragma unroll
;             for (int p = 0; p < 2; ++p) { const float cgv = bg[p] + wgt[0][p] * g2[p] + wgt[1][p] * g1[p] + wgt[2][p] * g0[p];
;                 const float cvv = bv[p] + wvl[0][p] * v2[p] + wvl[1][p] * v1[p] + wvl[2][p] * v0[p]; res[p] = gelu_t(cgv) * cvv;
;                 g2[p] = g1[p]; g1[p] = g0[p]; v2[p] = v1[p]; v1[p] = v0[p]; }
;             *(unsigned*)(UP + (size_t)row * FF2 + j0) = pk2(res[0], res[1]);
	v_lshlrev_b32_e32 v204, 16, v180
	v_and_b32_e32 v205, 0xffff0000, v180
	v_lshlrev_b32_e32 v206, 16, v181
	v_and_b32_e32 v207, 0xffff0000, v181
	v_pk_fma_f32 v[208:209], v[4:5], v[196:197], v[16:17]
	v_pk_fma_f32 v[210:211], v[6:7], v[198:199], v[18:19]
	v_pk_fma_f32 v[208:209], v[8:9], v[200:201], v[208:209]
	v_pk_fma_f32 v[210:211], v[10:11], v[202:203], v[210:211]
	v_pk_fma_f32 v[208:209], v[12:13], v[204:205], v[208:209]
	v_pk_fma_f32 v[210:211], v[14:15], v[206:207], v[210:211]
	v_pk_mul_f32 v[212:213], v[208:209], s[58:59]
	v_pk_mul_f32 v[212:213], v[208:209], v[212:213]
	v_pk_fma_f32 v[212:213], v[208:209], v[212:213], v[208:209]
	v_pk_mul_f32 v[212:213], v[212:213], s[60:61]
	v_pk_mul_f32 v[212:213], v[212:213], s[68:69]
	v_exp_f32_e32 v214, v212
	v_exp_f32_e32 v215, v213
	s_nop 0
	v_pk_add_f32 v[214:215], v[214:215], s[82:83]
	v_rcp_f32_e32 v214, v214
	v_rcp_f32_e32 v215, v215
	s_nop 0
	v_pk_mul_f32 v[212:213], v[208:209], v[214:215]
	v_pk_mul_f32 v[212:213], v[210:211], v[212:213]
	v_cvt_pk_bf16_f32 v216, v212, v213
	global_store_dword v2, v216, s[66:67]
	s_add_u32 s66, s66, 0x2c00
	s_addc_u32 s67, s67, 0
	s_waitcnt vmcnt(19)
	v_lshlrev_b32_e32 v196, 16, v182
	v_and_b32_e32 v197, 0xffff0000, v182
	v_lshlrev_b32_e32 v198, 16, v183
	v_and_b32_e32 v199, 0xffff0000, v183
	v_pk_fma_f32 v[208:209], v[4:5], v[200:201], v[16:17]
	v_pk_fma_f32 v[210:211], v[6:7], v[202:203], v[18:19]
	v_pk_fma_f32 v[208:209], v[8:9], v[204:205], v[208:209]
	v_pk_fma_f32 v[210:211], v[10:11], v[206:207], v[210:211]
	v_pk_fma_f32 v[208:209], v[12:13], v[196:197], v[208:209]
	v_pk_fma_f32 v[210:211], v[14:15], v[198:199], v[210:211]
	v_pk_mul_f32 v[212:213], v[208:209], s[58:59]
	v_pk_mul_f32 v[212:213], v[208:209], v[212:213]
	v_pk_fma_f32 v[212:213], v[208:209], v[212:213], v[208:209]
	v_pk_mul_f32 v[212:213], v[212:213], s[60:61]
	v_pk_mul_f32 v[212:213], v[212:213], s[68:69]
	v_exp_f32_e32 v214, v212
	v_exp_f32_e32 v215, v213
	s_nop 0
	v_pk_add_f32 v[214:215], v[214:215], s[82:83]
	v_rcp_f32_e32 v214, v214
	v_rcp_f32_e32 v215, v215
	s_nop 0
	v_pk_mul_f32 v[212:213], v[208:209], v[214:215]
	v_pk_mul_f32 v[212:213], v[210:211], v[212:213]
	v_cvt_pk_bf16_f32 v216, v212, v213
	global_store_dword v2, v216, s[66:67]
	s_add_u32 s66, s66, 0x2c00
	s_addc_u32 s67, s67, 0
	s_waitcnt vmcnt(18)
	v_lshlrev_b32_e32 v200, 16, v184
	v_and_b32_e32 v201, 0xffff0000, v184
	v_lshlrev_b32_e32 v202, 16, v185
	v_and_b32_e32 v203, 0xffff0000, v185
	v_pk_fma_f32 v[208:209], v[4:5], v[204:205], v[16:17]
	v_pk_fma_f32 v[210:211], v[6:7], v[206:207], v[18:19]
	v_pk_fma_f32 v[208:209], v[8:9], v[196:197], v[208:209]
	v_pk_fma_f32 v[210:211], v[10:11], v[198:199], v[210:211]
	v_pk_fma_f32 v[208:209], v[12:13], v[200:201], v[208:209]
	v_pk_fma_f32 v[210:211], v[14:15], v[202:203], v[210:211]
	v_pk_mul_f32 v[212:213], v[208:209], s[58:59]
	v_pk_mul_f32 v[212:213], v[208:209], v[212:213]
	v_pk_fma_f32 v[212:213], v[208:209], v[212:213], v[208:209]
	v_pk_mul_f32 v[212:213], v[212:213], s[60:61]
	v_pk_mul_f32 v[212:213], v[212:213], s[68:69]
	v_exp_f32_e32 v214, v212
	v_exp_f32_e32 v215, v213
	s_nop 0
	v_pk_add_f32 v[214:215], v[214:215], s[82:83]
	v_rcp_f32_e32 v214, v214
	v_rcp_f32_e32 v215, v215
	s_nop 0
	v_pk_mul_f32 v[212:213], v[208:209], v[214:215]
	v_pk_mul_f32 v[212:213], v[210:211], v[212:213]
	v_cvt_pk_bf16_f32 v216, v212, v213
	global_store_dword v2, v216, s[66:67]
	s_add_u32 s66, s66, 0x2c00
	s_addc_u32 s67, s67, 0
	s_waitcnt vmcnt(17)
	v_lshlrev_b32_e32 v204, 16, v186
	v_and_b32_e32 v205, 0xffff0000, v186
	v_lshlrev_b32_e32 v206, 16, v187
	v_and_b32_e32 v207, 0xffff0000, v187
	v_pk_fma_f32 v[208:209], v[4:5], v[196:197], v[16:17]
	v_pk_fma_f32 v[210:211], v[6:7], v[198:199], v[18:19]
	v_pk_fma_f32 v[208:209], v[8:9], v[200:201], v[208:209]
	v_pk_fma_f32 v[210:211], v[10:11], v[202:203], v[210:211]
	v_pk_fma_f32 v[208:209], v[12:13], v[204:205], v[208:209]
	v_pk_fma_f32 v[210:211], v[14:15], v[206:207], v[210:211]
	v_pk_mul_f32 v[212:213], v[208:209], s[58:59]
	v_pk_mul_f32 v[212:213], v[208:209], v[212:213]
	v_pk_fma_f32 v[212:213], v[208:209], v[212:213], v[208:209]
	v_pk_mul_f32 v[212:213], v[212:213], s[60:61]
	v_pk_mul_f32 v[212:213], v[212:213], s[68:69]
	v_exp_f32_e32 v214, v212
	v_exp_f32_e32 v215, v213
	s_nop 0
	v_pk_add_f32 v[214:215], v[214:215], s[82:83]
	v_rcp_f32_e32 v214, v214
	v_rcp_f32_e32 v215, v215
	s_nop 0
	v_pk_mul_f32 v[212:213], v[208:209], v[214:215]
	v_pk_mul_f32 v[212:213], v[210:211], v[212:213]
	v_cvt_pk_bf16_f32 v216, v212, v213
	global_store_dword v2, v216, s[66:67]
	s_add_u32 s66, s66, 0x2c00
	s_addc_u32 s67, s67, 0
	s_waitcnt vmcnt(16)
	v_lshlrev_b32_e32 v196, 16, v188
	v_and_b32_e32 v197, 0xffff0000, v188
	v_lshlrev_b32_e32 v198, 16, v189
	v_and_b32_e32 v199, 0xffff0000, v189
	v_pk_fma_f32 v[208:209], v[4:5], v[200:201], v[16:17]
	v_pk_fma_f32 v[210:211], v[6:7], v[202:203], v[18:19]
	v_pk_fma_f32 v[208:209], v[8:9], v[204:205], v[208:209]
	v_pk_fma_f32 v[210:211], v[10:11], v[206:207], v[210:211]
	v_pk_fma_f32 v[208:209], v[12:13], v[196:197], v[208:209]
	v_pk_fma_f32 v[210:211], v[14:15], v[198:199], v[210:211]
	v_pk_mul_f32 v[212:213], v[208:209], s[58:59]
	v_pk_mul_f32 v[212:213], v[208:209], v[212:213]
	v_pk_fma_f32 v[212:213], v[208:209], v[212:213], v[208:209]
	v_pk_mul_f32 v[212:213], v[212:213], s[60:61]
	v_pk_mul_f32 v[212:213], v[212:213], s[68:69]
	v_exp_f32_e32 v214, v212
	v_exp_f32_e32 v215, v213
	s_nop 0
	v_pk_add_f32 v[214:215], v[214:215], s[82:83]
	v_rcp_f32_e32 v214, v214
	v_rcp_f32_e32 v215, v215
	s_nop 0
	v_pk_mul_f32 v[212:213], v[208:209], v[214:215]
	v_pk_mul_f32 v[212:213], v[210:211], v[212:213]
	v_cvt_pk_bf16_f32 v216, v212, v213
	global_store_dword v2, v216, s[66:67]
	s_add_u32 s66, s66, 0x2c00
	s_addc_u32 s67, s67, 0
	s_waitcnt vmcnt(15)
; __device__ __forceinline__ float bf2f(unsigned b) { return __uint_as_float(b << 16); }
; __device__ __forceinline__ unsigned pk2(float lo, float hi) { unsigned r; asm("v_cvt_pk_bf16_f32 %0, %1, %2" : "=v"(r) : "v"(lo), "v"(hi)); return r; }
; __device__ __forceinline__ float gelu_t(float x) { return x * __builtin_amdgcn_rcpf(1.f + __expf(-1.5957691216057308f * (x + 0.044715f * x * x * x))); }
; __device__ __forceinline__ void act_item(int item, u16* UP, const u16* HALO, const float* sconv, const float* wconv, const float* bconv, float* out, int lane) {
;     ...
;     for (int tb = 0; tb < 64; tb += 16) {
;         unsigned gw[16], vw[16];
; #pragma unroll
;         for (int t = 0; t < 16; ++t) { const size_t row = (size_t)rb * 64 + tb + t; gw[t] = *(const unsigned*)(UP + row * FF2 + j0); vw[t] = *(const unsigned*)(UP + row * FF2 + FF + j0); }
; #pragma unroll
;         for (int t = 0; t < 16; ++t) {
;             const int row = rb * 64 + tb + t;
;             if (sample && (t & 3) == 0) { const int ns = (row - TP) >> 2; const float* s0 = sconv + (size_t)ns * 2 * FF2;
;                 const f32x2 a = *(const f32x2*)(s0 + j0), b = *(const f32x2*)(s0 + FF + j0), c = *(const f32x2*)(s0 + FF2 + j0), dd = *(const f32x2*)(s0 + FF2 + FF + j0);
;                 g2[0] = a.x; g2[1] = a.y; v2[0] = b.x; v2[1] = b.y; g1[0] = c.x; g1[1] = c.y; v1[0] = dd.x; v1[1] = dd.y; }
;             const float g0[2] = {bf2f(gw[t] & 0xffffu), bf2f(gw[t] >> 16)}, v0[2] = {bf2f(vw[t] & 0xffffu), bf2f(vw[t] >> 16)};
;             float res[2];
; #pragma unroll
;             for (int p = 0; p < 2; ++p) { const float cgv = bg[p] + wgt[0][p] * g2[p] + wgt[1][p] * g1[p] + wgt[2][p] * g0[p];
;                 const float cvv = bv[p] + wvl[0][p] * v2[p] + wvl[1][p] * v1[p] + wvl[2][p] * v0[p]; res[p] = gelu_t(cgv) * cvv;
;                 g2[p] = g1[p]; g1[p] = g0[p]; v2[p] = v1[p]; v1[p] = v0[p]; }
;             *(unsigned*)(UP + (size_t)row * FF2 + j0) = pk2(res[0], res[1]);
	v_lshlrev_b32_e32 v200, 16, v190
	v_and_b32_e32 v201, 0xffff0000, v190
	v_lshlrev_b32_e32 v202, 16, v191
	v_and_b32_e32 v203, 0xffff0000, v191
	v_pk_fma_f32 v[208:209], v[4:5], v[204:205], v[16:17]
	v_pk_fma_f32 v[210:211], v[6:7], v[206:207], v[18:19]
	v_pk_fma_f32 v[208:209], v[8:9], v[196:197], v[208:209]
	v_pk_fma_f32 v[210:211], v[10:11], v[198:199], v[210:211]
	v_pk_fma_f32 v[208:209], v[12:13], v[200:201], v[208:209]
	v_pk_fma_f32 v[210:211], v[14:15], v[202:203], v[210:211]
	v_pk_mul_f32 v[212:213], v[208:209], s[58:59]
	v_pk_mul_f32 v[212:213], v[208:209], v[212:213]
	v_pk_fma_f32 v[212:213], v[208:209], v[212:213], v[208:209]
	v_pk_mul_f32 v[212:213], v[212:213], s[60:61]
	v_pk_mul_f32 v[212:213], v[212:213], s[68:69]
	v_exp_f32_e32 v214, v212
	v_exp_f32_e32 v215, v213
	s_nop 0
	v_pk_add_f32 v[214:215], v[214:215], s[82:83]
	v_rcp_f32_e32 v214, v214
	v_rcp_f32_e32 v215, v215
	s_nop 0
	v_pk_mul_f32 v[212:213], v[208:209], v[214:215]
	v_pk_mul_f32 v[212:213], v[210:211], v[212:213]
	v_cvt_pk_bf16_f32 v216, v212, v213
	global_store_dword v2, v216, s[66:67]
	s_add_u32 s66, s66, 0x2c00
	s_addc_u32 s67, s67, 0
	global_load_dword v160, v2, s[64:65]
	global_load_dword v161, v3, s[64:65]
	s_add_u32 s64, s64, 0x2c00
	s_addc_u32 s65, s65, 0
	global_load_dword v162, v2, s[64:65]
	global_load_dword v163, v3, s[64:65]
	s_add_u32 s64, s64, 0x2c00
	s_addc_u32 s65, s65, 0
	global_load_dword v164, v2, s[64:65]
	global_load_dword v165, v3, s[64:65]
	s_add_u32 s64, s64, 0x2c00
	s_addc_u32 s65, s65, 0
	global_load_dword v166, v2, s[64:65]
	global_load_dword v167, v3, s[64:65]
	s_add_u32 s64, s64, 0x2c00
	s_addc_u32 s65, s65, 0
	global_load_dword v168, v2, s[64:65]
	global_load_dword v169, v3, s[64:65]
	s_add_u32 s64, s64, 0x2c00
	s_addc_u32 s65, s65, 0
	global_load_dword v170, v2, s[64:65]
	global_load_dword v171, v3, s[64:65]
	s_add_u32 s64, s64, 0x2c00
	s_addc_u32 s65, s65, 0
	global_load_dword v172, v2, s[64:65]
	global_load_dword v173, v3, s[64:65]
	s_add_u32 s64, s64, 0x2c00
	s_addc_u32 s65, s65, 0
	global_load_dword v174, v2, s[64:65]
	global_load_dword v175, v3, s[64:65]
	s_add_u32 s64, s64, 0x2c00
	s_addc_u32 s65, s65, 0
	global_load_dword v176, v2, s[64:65]
	global_load_dword v177, v3, s[64:65]
	s_add_u32 s64, s64, 0x2c00
	s_addc_u32 s65, s65, 0
	global_load_dword v178, v2, s[64:65]
	global_load_dword v179, v3, s[64:65]
	s_add_u32 s64, s64, 0x2c00
	s_addc_u32 s65, s65, 0
	global_load_dword v180, v2, s[64:65]
	global_load_dword v181, v3, s[64:65]
	s_add_u32 s64, s64, 0x2c00
	s_addc_u32 s65, s65, 0
	global_load_dword v182, v2, s[64:65]
	global_load_dword v183, v3, s[64:65]
	s_add_u32 s64, s64, 0x2c00
	s_addc_u32 s65, s65, 0
	global_load_dword v184, v2, s[64:65]
	global_load_dword v185, v3, s[64:65]
	s_add_u32 s64, s64, 0x2c00
	s_addc_u32 s65, s65, 0
	global_load_dword v186, v2, s[64:65]
	global_load_dword v187, v3, s[64:65]
	s_add_u32 s64, s64, 0x2c00
	s_addc_u32 s65, s65, 0
	global_load_dword v188, v2, s[64:65]
	global_load_dword v189, v3, s[64:65]
	s_add_u32 s64, s64, 0x2c00
	s_addc_u32 s65, s65, 0
	global_load_dword v190, v2, s[64:65]
	global_load_dword v191, v3, s[64:65]
	s_add_u32 s64, s64, 0x2c00
	s_addc_u32 s65, s65, 0
	s_waitcnt vmcnt(30)
	v_lshlrev_b32_e32 v204, 16, v160
	v_and_b32_e32 v205, 0xffff0000, v160
	v_lshlrev_b32_e32 v206, 16, v161
	v_and_b32_e32 v207, 0xffff0000, v161
	v_pk_fma_f32 v[208:209], v[4:5], v[196:197], v[16:17]
	v_pk_fma_f32 v[210:211], v[6:7], v[198:199], v[18:19]
	v_pk_fma_f32 v[208:209], v[8:9], v[200:201], v[208:209]
	v_pk_fma_f32 v[210:211], v[10:11], v[202:203], v[210:211]
	v_pk_fma_f32 v[208:209], v[12:13], v[204:205], v[208:209]
	v_pk_fma_f32 v[210:211], v[14:15], v[206:207], v[210:211]
	v_pk_mul_f32 v[212:213], v[208:209], s[58:59]
	v_pk_mul_f32 v[212:213], v[208:209], v[212:213]
	v_pk_fma_f32 v[212:213], v[208:209], v[212:213], v[208:209]
	v_pk_mul_f32 v[212:213], v[212:213], s[60:61]
	v_pk_mul_f32 v[212:213], v[212:213], s[68:69]
	v_exp_f32_e32 v214, v212
	v_exp_f32_e32 v215, v213
	s_nop 0
	v_pk_add_f32 v[214:215], v[214:215], s[82:83]
	v_rcp_f32_e32 v214, v214
	v_rcp_f32_e32 v215, v215
	s_nop 0
	v_pk_mul_f32 v[212:213], v[208:209], v[214:215]
	v_pk_mul_f32 v[212:213], v[210:211], v[212:213]
	v_cvt_pk_bf16_f32 v216, v212, v213
	global_store_dword v2, v216, s[66:67]
	s_add_u32 s66, s66, 0x2c00
	s_addc_u32 s67, s67, 0
	s_waitcnt vmcnt(29)
	v_lshlrev_b32_e32 v196, 16, v162
	v_and_b32_e32 v197, 0xffff0000, v162
	v_lshlrev_b32_e32 v198, 16, v163
	v_and_b32_e32 v199, 0xffff0000, v163
	v_pk_fma_f32 v[208:209], v[4:5], v[200:201], v[16:17]
	v_pk_fma_f32 v[210:211], v[6:7], v[202:203], v[18:19]
	v_pk_fma_f32 v[208:209], v[8:9], v[204:205], v[208:209]
	v_pk_fma_f32 v[210:211], v[10:11], v[206:207], v[210:211]
	v_pk_fma_f32 v[208:209], v[12:13], v[196:197], v[208:209]
	v_pk_fma_f32 v[210:211], v[14:15], v[198:199], v[210:211]
	v_pk_mul_f32 v[212:213], v[208:209], s[58:59]
	v_pk_mul_f32 v[212:213], v[208:209], v[212:213]
	v_pk_fma_f32 v[212:213], v[208:209], v[212:213], v[208:209]
	v_pk_mul_f32 v[212:213], v[212:213], s[60:61]
	v_pk_mul_f32 v[212:213], v[212:213], s[68:69]
	v_exp_f32_e32 v214, v212
	v_exp_f32_e32 v215, v213
	s_nop 0
	v_pk_add_f32 v[214:215], v[214:215], s[82:83]
	v_rcp_f32_e32 v214, v214
	v_rcp_f32_e32 v215, v215
	s_nop 0
	v_pk_mul_f32 v[212:213], v[208:209], v[214:215]
	v_pk_mul_f32 v[212:213], v[210:211], v[212:213]
	v_cvt_pk_bf16_f32 v216, v212, v213
	global_store_dword v2, v216, s[66:67]
	s_add_u32 s66, s66, 0x2c00
	s_addc_u32 s67, s67, 0
	s_waitcnt vmcnt(28)
; __device__ __forceinline__ float bf2f(unsigned b) { return __uint_as_float(b << 16); }
; __device__ __forceinline__ unsigned pk2(float lo, float hi) { unsigned r; asm("v_cvt_pk_bf16_f32 %0, %1, %2" : "=v"(r) : "v"(lo), "v"(hi)); return r; }
; __device__ __forceinline__ float gelu_t(float x) { return x * __builtin_amdgcn_rcpf(1.f + __expf(-1.5957691216057308f * (x + 0.044715f * x * x * x))); }
; __device__ __forceinline__ void act_item(int item, u16* UP, const u16* HALO, const float* sconv, const float* wconv, const float* bconv, float* out, int lane) {
;     ...
;     for (int tb = 0; tb < 64; tb += 16) {
;         unsigned gw[16], vw[16];
; #pragma unroll
;         for (int t = 0; t < 16; ++t) { const size_t row = (size_t)rb * 64 + tb + t; gw[t] = *(const unsigned*)(UP + row * FF2 + j0); vw[t] = *(const unsigned*)(UP + row * FF2 + FF + j0); }
; #pragma unroll
;         for (int t = 0; t < 16; ++t) {
;             const int row = rb * 64 + tb + t;
;             if (sample && (t & 3) == 0) { const int ns = (row - TP) >> 2; const float* s0 = sconv + (size_t)ns * 2 * FF2;
;                 const f32x2 a = *(const f32x2*)(s0 + j0), b = *(const f32x2*)(s0 + FF + j0), c = *(const f32x2*)(s0 + FF2 + j0), dd = *(const f32x2*)(s0 + FF2 + FF + j0);
;                 g2[0] = a.x; g2[1] = a.y; v2[0] = b.x; v2[1] = b.y; g1[0] = c.x; g1[1] = c.y; v1[0] = dd.x; v1[1] = dd.y; }
;             const float g0[2] = {bf2f(gw[t] & 0xffffu), bf2f(gw[t] >> 16)}, v0[2] = {bf2f(vw[t] & 0xffffu), bf2f(vw[t] >> 16)};
;             float res[2];
; #pragma unroll
;             for (int p = 0; p < 2; ++p) { const float cgv = bg[p] + wgt[0][p] * g2[p] + wgt[1][p] * g1[p] + wgt[2][p] * g0[p];
;                 const float cvv = bv[p] + wvl[0][p] * v2[p] + wvl[1][p] * v1[p] + wvl[2][p] * v0[p]; res[p] = gelu_t(cgv) * cvv;
;                 g2[p] = g1[p]; g1[p] = g0[p]; v2[p] = v1[p]; v1[p] = v0[p]; }
;             *(unsigned*)(UP + (size_t)row * FF2 + j0) = pk2(res[0], res[1]);
	v_lshlrev_b32_e32 v200, 16, v164
	v_and_b32_e32 v201, 0xffff0000, v164
	v_lshlrev_b32_e32 v202, 16, v165
	v_and_b32_e32 v203, 0xffff0000, v165
	v_pk_fma_f32 v[208:209], v[4:5], v[204:205], v[16:17]
	v_pk_fma_f32 v[210:211], v[6:7], v[206:207], v[18:19]
	v_pk_fma_f32 v[208:209], v[8:9], v[196:197], v[208:209]
	v_pk_fma_f32 v[210:211], v[10:11], v[198:199], v[210:211]
	v_pk_fma_f32 v[208:209], v[12:13], v[200:201], v[208:209]
	v_pk_fma_f32 v[210:211], v[14:15], v[202:203], v[210:211]
	v_pk_mul_f32 v[212:213], v[208:209], s[58:59]
	v_pk_mul_f32 v[212:213], v[208:209], v[212:213]
	v_pk_fma_f32 v[212:213], v[208:209], v[212:213], v[208:209]
	v_pk_mul_f32 v[212:213], v[212:213], s[60:61]
	v_pk_mul_f32 v[212:213], v[212:213], s[68:69]
	v_exp_f32_e32 v214, v212
	v_exp_f32_e32 v215, v213
	s_nop 0
	v_pk_add_f32 v[214:215], v[214:215], s[82:83]
	v_rcp_f32_e32 v214, v214
	v_rcp_f32_e32 v215, v215
	s_nop 0
	v_pk_mul_f32 v[212:213], v[208:209], v[214:215]
	v_pk_mul_f32 v[212:213], v[210:211], v[212:213]
	v_cvt_pk_bf16_f32 v216, v212, v213
	global_store_dword v2, v216, s[66:67]
	s_add_u32 s66, s66, 0x2c00
	s_addc_u32 s67, s67, 0
	s_waitcnt vmcnt(27)
	v_lshlrev_b32_e32 v204, 16, v166
	v_and_b32_e32 v205, 0xffff0000, v166
	v_lshlrev_b32_e32 v206, 16, v167
	v_and_b32_e32 v207, 0xffff0000, v167
	v_pk_fma_f32 v[208:209], v[4:5], v[196:197], v[16:17]
	v_pk_fma_f32 v[210:211], v[6:7], v[198:199], v[18:19]
	v_pk_fma_f32 v[208:209], v[8:9], v[200:201], v[208:209]
	v_pk_fma_f32 v[210:211], v[10:11], v[202:203], v[210:211]
	v_pk_fma_f32 v[208:209], v[12:13], v[204:205], v[208:209]
	v_pk_fma_f32 v[210:211], v[14:15], v[206:207], v[210:211]
	v_pk_mul_f32 v[212:213], v[208:209], s[58:59]
	v_pk_mul_f32 v[212:213], v[208:209], v[212:213]
	v_pk_fma_f32 v[212:213], v[208:209], v[212:213], v[208:209]
	v_pk_mul_f32 v[212:213], v[212:213], s[60:61]
	v_pk_mul_f32 v[212:213], v[212:213], s[68:69]
	v_exp_f32_e32 v214, v212
	v_exp_f32_e32 v215, v213
	s_nop 0
	v_pk_add_f32 v[214:215], v[214:215], s[82:83]
	v_rcp_f32_e32 v214, v214
	v_rcp_f32_e32 v215, v215
	s_nop 0
	v_pk_mul_f32 v[212:213], v[208:209], v[214:215]
	v_pk_mul_f32 v[212:213], v[210:211], v[212:213]
	v_cvt_pk_bf16_f32 v216, v212, v213
	global_store_dword v2, v216, s[66:67]
	s_add_u32 s66, s66, 0x2c00
	s_addc_u32 s67, s67, 0
	s_waitcnt vmcnt(26)
	v_lshlrev_b32_e32 v196, 16, v168
	v_and_b32_e32 v197, 0xffff0000, v168
	v_lshlrev_b32_e32 v198, 16, v169
	v_and_b32_e32 v199, 0xffff0000, v169
	v_pk_fma_f32 v[208:209], v[4:5], v[200:201], v[16:17]
	v_pk_fma_f32 v[210:211], v[6:7], v[202:203], v[18:19]
	v_pk_fma_f32 v[208:209], v[8:9], v[204:205], v[208:209]
	v_pk_fma_f32 v[210:211], v[10:11], v[206:207], v[210:211]
	v_pk_fma_f32 v[208:209], v[12:13], v[196:197], v[208:209]
	v_pk_fma_f32 v[210:211], v[14:15], v[198:199], v[210:211]
	v_pk_mul_f32 v[212:213], v[208:209], s[58:59]
	v_pk_mul_f32 v[212:213], v[208:209], v[212:213]
	v_pk_fma_f32 v[212:213], v[208:209], v[212:213], v[208:209]
	v_pk_mul_f32 v[212:213], v[212:213], s[60:61]
	v_pk_mul_f32 v[212:213], v[212:213], s[68:69]
	v_exp_f32_e32 v214, v212
	v_exp_f32_e32 v215, v213
	s_nop 0
	v_pk_add_f32 v[214:215], v[214:215], s[82:83]
	v_rcp_f32_e32 v214, v214
	v_rcp_f32_e32 v215, v215
	s_nop 0
	v_pk_mul_f32 v[212:213], v[208:209], v[214:215]
	v_pk_mul_f32 v[212:213], v[210:211], v[212:213]
	v_cvt_pk_bf16_f32 v216, v212, v213
	global_store_dword v2, v216, s[66:67]
	s_add_u32 s66, s66, 0x2c00
	s_addc_u32 s67, s67, 0
	s_waitcnt vmcnt(25)
	v_lshlrev_b32_e32 v200, 16, v170
	v_and_b32_e32 v201, 0xffff0000, v170
	v_lshlrev_b32_e32 v202, 16, v171
	v_and_b32_e32 v203, 0xffff0000, v171
	v_pk_fma_f32 v[208:209], v[4:5], v[204:205], v[16:17]
	v_pk_fma_f32 v[210:211], v[6:7], v[206:207], v[18:19]
	v_pk_fma_f32 v[208:209], v[8:9], v[196:197], v[208:209]
	v_pk_fma_f32 v[210:211], v[10:11], v[198:199], v[210:211]
	v_pk_fma_f32 v[208:209], v[12:13], v[200:201], v[208:209]
	v_pk_fma_f32 v[210:211], v[14:15], v[202:203], v[210:211]
	v_pk_mul_f32 v[212:213], v[208:209], s[58:59]
	v_pk_mul_f32 v[212:213], v[208:209], v[212:213]
	v_pk_fma_f32 v[212:213], v[208:209], v[212:213], v[208:209]
	v_pk_mul_f32 v[212:213], v[212:213], s[60:61]
	v_pk_mul_f32 v[212:213], v[212:213], s[68:69]
	v_exp_f32_e32 v214, v212
	v_exp_f32_e32 v215, v213
	s_nop 0
	v_pk_add_f32 v[214:215], v[214:215], s[82:83]
	v_rcp_f32_e32 v214, v214
	v_rcp_f32_e32 v215, v215
	s_nop 0
	v_pk_mul_f32 v[212:213], v[208:209], v[214:215]
	v_pk_mul_f32 v[212:213], v[210:211], v[212:213]
	v_cvt_pk_bf16_f32 v216, v212, v213
	global_store_dword v2, v216, s[66:67]
	s_add_u32 s66, s66, 0x2c00
	s_addc_u32 s67, s67, 0
	s_waitcnt vmcnt(24)
	v_lshlrev_b32_e32 v204, 16, v172
	v_and_b32_e32 v205, 0xffff0000, v172
	v_lshlrev_b32_e32 v206, 16, v173
	v_and_b32_e32 v207, 0xffff0000, v173
	v_pk_fma_f32 v[208:209], v[4:5], v[196:197], v[16:17]
	v_pk_fma_f32 v[210:211], v[6:7], v[198:199], v[18:19]
	v_pk_fma_f32 v[208:209], v[8:9], v[200:201], v[208:209]
	v_pk_fma_f32 v[210:211], v[10:11], v[202:203], v[210:211]
	v_pk_fma_f32 v[208:209], v[12:13], v[204:205], v[208:209]
	v_pk_fma_f32 v[210:211], v[14:15], v[206:207], v[210:211]
	v_pk_mul_f32 v[212:213], v[208:209], s[58:59]
	v_pk_mul_f32 v[212:213], v[208:209], v[212:213]
	v_pk_fma_f32 v[212:213], v[208:209], v[212:213], v[208:209]
	v_pk_mul_f32 v[212:213], v[212:213], s[60:61]
	v_pk_mul_f32 v[212:213], v[212:213], s[68:69]
	v_exp_f32_e32 v214, v212
	v_exp_f32_e32 v215, v213
	s_nop 0
	v_pk_add_f32 v[214:215], v[214:215], s[82:83]
	v_rcp_f32_e32 v214, v214
	v_rcp_f32_e32 v215, v215
	s_nop 0
	v_pk_mul_f32 v[212:213], v[208:209], v[214:215]
	v_pk_mul_f32 v[212:213], v[210:211], v[212:213]
	v_cvt_pk_bf16_f32 v216, v212, v213
	global_store_dword v2, v216, s[66:67]
	s_add_u32 s66, s66, 0x2c00
	s_addc_u32 s67, s67, 0
	s_waitcnt vmcnt(23)
; __device__ __forceinline__ float bf2f(unsigned b) { return __uint_as_float(b << 16); }
; __device__ __forceinline__ unsigned pk2(float lo, float hi) { unsigned r; asm("v_cvt_pk_bf16_f32 %0, %1, %2" : "=v"(r) : "v"(lo), "v"(hi)); return r; }
; __device__ __forceinline__ float gelu_t(float x) { return x * __builtin_amdgcn_rcpf(1.f + __expf(-1.5957691216057308f * (x + 0.044715f * x * x * x))); }
; __device__ __forceinline__ void act_item(int item, u16* UP, const u16* HALO, const float* sconv, const float* wconv, const float* bconv, float* out, int lane) {
;     ...
;     for (int tb = 0; tb < 64; tb += 16) {
;         unsigned gw[16], vw[16];
; #pragma unroll
;         for (int t = 0; t < 16; ++t) { const size_t row = (size_t)rb * 64 + tb + t; gw[t] = *(const unsigned*)(UP + row * FF2 + j0); vw[t] = *(const unsigned*)(UP + row * FF2 + FF + j0); }
; #pragma unroll
;         for (int t = 0; t < 16; ++t) {
;             const int row = rb * 64 + tb + t;
;             if (sample && (t & 3) == 0) { const int ns = (row - TP) >> 2; const float* s0 = sconv + (size_t)ns * 2 * FF2;
;                 const f32x2 a = *(const f32x2*)(s0 + j0), b = *(const f32x2*)(s0 + FF + j0), c = *(const f32x2*)(s0 + FF2 + j0), dd = *(const f32x2*)(s0 + FF2 + FF + j0);
;                 g2[0] = a.x; g2[1] = a.y; v2[0] = b.x; v2[1] = b.y; g1[0] = c.x; g1[1] = c.y; v1[0] = dd.x; v1[1] = dd.y; }
;             const float g0[2] = {bf2f(gw[t] & 0xffffu), bf2f(gw[t] >> 16)}, v0[2] = {bf2f(vw[t] & 0xffffu), bf2f(vw[t] >> 16)};
;             float res[2];
; #pragma unroll
;             for (int p = 0; p < 2; ++p) { const float cgv = bg[p] + wgt[0][p] * g2[p] + wgt[1][p] * g1[p] + wgt[2][p] * g0[p];
;                 const float cvv = bv[p] + wvl[0][p] * v2[p] + wvl[1][p] * v1[p] + wvl[2][p] * v0[p]; res[p] = gelu_t(cgv) * cvv;
;                 g2[p] = g1[p]; g1[p] = g0[p]; v2[p] = v1[p]; v1[p] = v0[p]; }
;             *(unsigned*)(UP + (size_t)row * FF2 + j0) = pk2(res[0], res[1]);
	v_lshlrev_b32_e32 v196, 16, v174
	v_and_b32_e32 v197, 0xffff0000, v174
	v_lshlrev_b32_e32 v198, 16, v175
	v_and_b32_e32 v199, 0xffff0000, v175
	v_pk_fma_f32 v[208:209], v[4:5], v[200:201], v[16:17]
	v_pk_fma_f32 v[210:211], v[6:7], v[202:203], v[18:19]
	v_pk_fma_f32 v[208:209], v[8:9], v[204:205], v[208:209]
	v_pk_fma_f32 v[210:211], v[10:11], v[206:207], v[210:211]
	v_pk_fma_f32 v[208:209], v[12:13], v[196:197], v[208:209]
	v_pk_fma_f32 v[210:211], v[14:15], v[198:199], v[210:211]
	v_pk_mul_f32 v[212:213], v[208:209], s[58:59]
	v_pk_mul_f32 v[212:213], v[208:209], v[212:213]
	v_pk_fma_f32 v[212:213], v[208:209], v[212:213], v[208:209]
	v_pk_mul_f32 v[212:213], v[212:213], s[60:61]
	v_pk_mul_f32 v[212:213], v[212:213], s[68:69]
	v_exp_f32_e32 v214, v212
	v_exp_f32_e32 v215, v213
	s_nop 0
	v_pk_add_f32 v[214:215], v[214:215], s[82:83]
	v_rcp_f32_e32 v214, v214
	v_rcp_f32_e32 v215, v215
	s_nop 0
	v_pk_mul_f32 v[212:213], v[208:209], v[214:215]
	v_pk_mul_f32 v[212:213], v[210:211], v[212:213]
	v_cvt_pk_bf16_f32 v216, v212, v213
	global_store_dword v2, v216, s[66:67]
	s_add_u32 s66, s66, 0x2c00
	s_addc_u32 s67, s67, 0
	s_waitcnt vmcnt(22)
	v_lshlrev_b32_e32 v200, 16, v176
	v_and_b32_e32 v201, 0xffff0000, v176
	v_lshlrev_b32_e32 v202, 16, v177
	v_and_b32_e32 v203, 0xffff0000, v177
	v_pk_fma_f32 v[208:209], v[4:5], v[204:205], v[16:17]
	v_pk_fma_f32 v[210:211], v[6:7], v[206:207], v[18:19]
	v_pk_fma_f32 v[208:209], v[8:9], v[196:197], v[208:209]
	v_pk_fma_f32 v[210:211], v[10:11], v[198:199], v[210:211]
	v_pk_fma_f32 v[208:209], v[12:13], v[200:201], v[208:209]
	v_pk_fma_f32 v[210:211], v[14:15], v[202:203], v[210:211]
	v_pk_mul_f32 v[212:213], v[208:209], s[58:59]
	v_pk_mul_f32 v[212:213], v[208:209], v[212:213]
	v_pk_fma_f32 v[212:213], v[208:209], v[212:213], v[208:209]
	v_pk_mul_f32 v[212:213], v[212:213], s[60:61]
	v_pk_mul_f32 v[212:213], v[212:213], s[68:69]
	v_exp_f32_e32 v214, v212
	v_exp_f32_e32 v215, v213
	s_nop 0
	v_pk_add_f32 v[214:215], v[214:215], s[82:83]
	v_rcp_f32_e32 v214, v214
	v_rcp_f32_e32 v215, v215
	s_nop 0
	v_pk_mul_f32 v[212:213], v[208:209], v[214:215]
	v_pk_mul_f32 v[212:213], v[210:211], v[212:213]
	v_cvt_pk_bf16_f32 v216, v212, v213
	global_store_dword v2, v216, s[66:67]
	s_add_u32 s66, s66, 0x2c00
	s_addc_u32 s67, s67, 0
	s_waitcnt vmcnt(21)
	v_lshlrev_b32_e32 v204, 16, v178
	v_and_b32_e32 v205, 0xffff0000, v178
	v_lshlrev_b32_e32 v206, 16, v179
	v_and_b32_e32 v207, 0xffff0000, v179
	v_pk_fma_f32 v[208:209], v[4:5], v[196:197], v[16:17]
	v_pk_fma_f32 v[210:211], v[6:7], v[198:199], v[18:19]
	v_pk_fma_f32 v[208:209], v[8:9], v[200:201], v[208:209]
	v_pk_fma_f32 v[210:211], v[10:11], v[202:203], v[210:211]
	v_pk_fma_f32 v[208:209], v[12:13], v[204:205], v[208:209]
	v_pk_fma_f32 v[210:211], v[14:15], v[206:207], v[210:211]
	v_pk_mul_f32 v[212:213], v[208:209], s[58:59]
	v_pk_mul_f32 v[212:213], v[208:209], v[212:213]
	v_pk_fma_f32 v[212:213], v[208:209], v[212:213], v[208:209]
	v_pk_mul_f32 v[212:213], v[212:213], s[60:61]
	v_pk_mul_f32 v[212:213], v[212:213], s[68:69]
	v_exp_f32_e32 v214, v212
	v_exp_f32_e32 v215, v213
	s_nop 0
	v_pk_add_f32 v[214:215], v[214:215], s[82:83]
	v_rcp_f32_e32 v214, v214
	v_rcp_f32_e32 v215, v215
	s_nop 0
	v_pk_mul_f32 v[212:213], v[208:209], v[214:215]
	v_pk_mul_f32 v[212:213], v[210:211], v[212:213]
	v_cvt_pk_bf16_f32 v216, v212, v213
	global_store_dword v2, v216, s[66:67]
	s_add_u32 s66, s66, 0x2c00
	s_addc_u32 s67, s67, 0
	s_waitcnt vmcnt(20)
	v_lshlrev_b32_e32 v196, 16, v180
	v_and_b32_e32 v197, 0xffff0000, v180
	v_lshlrev_b32_e32 v198, 16, v181
	v_and_b32_e32 v199, 0xffff0000, v181
	v_pk_fma_f32 v[208:209], v[4:5], v[200:201], v[16:17]
	v_pk_fma_f32 v[210:211], v[6:7], v[202:203], v[18:19]
	v_pk_fma_f32 v[208:209], v[8:9], v[204:205], v[208:209]
	v_pk_fma_f32 v[210:211], v[10:11], v[206:207], v[210:211]
	v_pk_fma_f32 v[208:209], v[12:13], v[196:197], v[208:209]
	v_pk_fma_f32 v[210:211], v[14:15], v[198:199], v[210:211]
	v_pk_mul_f32 v[212:213], v[208:209], s[58:59]
	v_pk_mul_f32 v[212:213], v[208:209], v[212:213]
	v_pk_fma_f32 v[212:213], v[208:209], v[212:213], v[208:209]
	v_pk_mul_f32 v[212:213], v[212:213], s[60:61]
	v_pk_mul_f32 v[212:213], v[212:213], s[68:69]
	v_exp_f32_e32 v214, v212
	v_exp_f32_e32 v215, v213
	s_nop 0
	v_pk_add_f32 v[214:215], v[214:215], s[82:83]
	v_rcp_f32_e32 v214, v214
	v_rcp_f32_e32 v215, v215
	s_nop 0
	v_pk_mul_f32 v[212:213], v[208:209], v[214:215]
	v_pk_mul_f32 v[212:213], v[210:211], v[212:213]
	v_cvt_pk_bf16_f32 v216, v212, v213
	global_store_dword v2, v216, s[66:67]
	s_add_u32 s66, s66, 0x2c00
	s_addc_u32 s67, s67, 0
	s_waitcnt vmcnt(19)
	v_lshlrev_b32_e32 v200, 16, v182
	v_and_b32_e32 v201, 0xffff0000, v182
	v_lshlrev_b32_e32 v202, 16, v183
	v_and_b32_e32 v203, 0xffff0000, v183
	v_pk_fma_f32 v[208:209], v[4:5], v[204:205], v[16:17]
	v_pk_fma_f32 v[210:211], v[6:7], v[206:207], v[18:19]
	v_pk_fma_f32 v[208:209], v[8:9], v[196:197], v[208:209]
	v_pk_fma_f32 v[210:211], v[10:11], v[198:199], v[210:211]
	v_pk_fma_f32 v[208:209], v[12:13], v[200:201], v[208:209]
	v_pk_fma_f32 v[210:211], v[14:15], v[202:203], v[210:211]
	v_pk_mul_f32 v[212:213], v[208:209], s[58:59]
	v_pk_mul_f32 v[212:213], v[208:209], v[212:213]
	v_pk_fma_f32 v[212:213], v[208:209], v[212:213], v[208:209]
	v_pk_mul_f32 v[212:213], v[212:213], s[60:61]
	v_pk_mul_f32 v[212:213], v[212:213], s[68:69]
	v_exp_f32_e32 v214, v212
	v_exp_f32_e32 v215, v213
	s_nop 0
	v_pk_add_f32 v[214:215], v[214:215], s[82:83]
	v_rcp_f32_e32 v214, v214
	v_rcp_f32_e32 v215, v215
	s_nop 0
	v_pk_mul_f32 v[212:213], v[208:209], v[214:215]
	v_pk_mul_f32 v[212:213], v[210:211], v[212:213]
	v_cvt_pk_bf16_f32 v216, v212, v213
	global_store_dword v2, v216, s[66:67]
	s_add_u32 s66, s66, 0x2c00
	s_addc_u32 s67, s67, 0
	s_waitcnt vmcnt(18)
; __device__ __forceinline__ float bf2f(unsigned b) { return __uint_as_float(b << 16); }
; __device__ __forceinline__ unsigned pk2(float lo, float hi) { unsigned r; asm("v_cvt_pk_bf16_f32 %0, %1, %2" : "=v"(r) : "v"(lo), "v"(hi)); return r; }
; __device__ __forceinline__ float gelu_t(float x) { return x * __builtin_amdgcn_rcpf(1.f + __expf(-1.5957691216057308f * (x + 0.044715f * x * x * x))); }
; __device__ __forceinline__ void act_item(int item, u16* UP, const u16* HALO, const float* sconv, const float* wconv, const float* bconv, float* out, int lane) {
;     ...
;     for (int tb = 0; tb < 64; tb += 16) {
;         unsigned gw[16], vw[16];
; #pragma unroll
;         for (int t = 0; t < 16; ++t) { const size_t row = (size_t)rb * 64 + tb + t; gw[t] = *(const unsigned*)(UP + row * FF2 + j0); vw[t] = *(const unsigned*)(UP + row * FF2 + FF + j0); }
; #pragma unroll
;         for (int t = 0; t < 16; ++t) {
;             const int row = rb * 64 + tb + t;
;             if (sample && (t & 3) == 0) { const int ns = (row - TP) >> 2; const float* s0 = sconv + (size_t)ns * 2 * FF2;
;                 const f32x2 a = *(const f32x2*)(s0 + j0), b = *(const f32x2*)(s0 + FF + j0), c = *(const f32x2*)(s0 + FF2 + j0), dd = *(const f32x2*)(s0 + FF2 + FF + j0);
;                 g2[0] = a.x; g2[1] = a.y; v2[0] = b.x; v2[1] = b.y; g1[0] = c.x; g1[1] = c.y; v1[0] = dd.x; v1[1] = dd.y; }
;             const float g0[2] = {bf2f(gw[t] & 0xffffu), bf2f(gw[t] >> 16)}, v0[2] = {bf2f(vw[t] & 0xffffu), bf2f(vw[t] >> 16)};
;             float res[2];
; #pragma unroll
;             for (int p = 0; p < 2; ++p) { const float cgv = bg[p] + wgt[0][p] * g2[p] + wgt[1][p] * g1[p] + wgt[2][p] * g0[p];
;                 const float cvv = bv[p] + wvl[0][p] * v2[p] + wvl[1][p] * v1[p] + wvl[2][p] * v0[p]; res[p] = gelu_t(cgv) * cvv;
;                 g2[p] = g1[p]; g1[p] = g0[p]; v2[p] = v1[p]; v1[p] = v0[p]; }
;             *(unsigned*)(UP + (size_t)row * FF2 + j0) = pk2(res[0], res[1]);
	v_lshlrev_b32_e32 v204, 16, v184
	v_and_b32_e32 v205, 0xffff0000, v184
	v_lshlrev_b32_e32 v206, 16, v185
	v_and_b32_e32 v207, 0xffff0000, v185
	v_pk_fma_f32 v[208:209], v[4:5], v[196:197], v[16:17]
	v_pk_fma_f32 v[210:211], v[6:7], v[198:199], v[18:19]
	v_pk_fma_f32 v[208:209], v[8:9], v[200:201], v[208:209]
	v_pk_fma_f32 v[210:211], v[10:11], v[202:203], v[210:211]
	v_pk_fma_f32 v[208:209], v[12:13], v[204:205], v[208:209]
	v_pk_fma_f32 v[210:211], v[14:15], v[206:207], v[210:211]
	v_pk_mul_f32 v[212:213], v[208:209], s[58:59]
	v_pk_mul_f32 v[212:213], v[208:209], v[212:213]
	v_pk_fma_f32 v[212:213], v[208:209], v[212:213], v[208:209]
	v_pk_mul_f32 v[212:213], v[212:213], s[60:61]
	v_pk_mul_f32 v[212:213], v[212:213], s[68:69]
	v_exp_f32_e32 v214, v212
	v_exp_f32_e32 v215, v213
	s_nop 0
	v_pk_add_f32 v[214:215], v[214:215], s[82:83]
	v_rcp_f32_e32 v214, v214
	v_rcp_f32_e32 v215, v215
	s_nop 0
	v_pk_mul_f32 v[212:213], v[208:209], v[214:215]
	v_pk_mul_f32 v[212:213], v[210:211], v[212:213]
	v_cvt_pk_bf16_f32 v216, v212, v213
	global_store_dword v2, v216, s[66:67]
	s_add_u32 s66, s66, 0x2c00
	s_addc_u32 s67, s67, 0
	s_waitcnt vmcnt(17)
	v_lshlrev_b32_e32 v196, 16, v186
	v_and_b32_e32 v197, 0xffff0000, v186
	v_lshlrev_b32_e32 v198, 16, v187
	v_and_b32_e32 v199, 0xffff0000, v187
	v_pk_fma_f32 v[208:209], v[4:5], v[200:201], v[16:17]
	v_pk_fma_f32 v[210:211], v[6:7], v[202:203], v[18:19]
	v_pk_fma_f32 v[208:209], v[8:9], v[204:205], v[208:209]
	v_pk_fma_f32 v[210:211], v[10:11], v[206:207], v[210:211]
	v_pk_fma_f32 v[208:209], v[12:13], v[196:197], v[208:209]
	v_pk_fma_f32 v[210:211], v[14:15], v[198:199], v[210:211]
	v_pk_mul_f32 v[212:213], v[208:209], s[58:59]
	v_pk_mul_f32 v[212:213], v[208:209], v[212:213]
	v_pk_fma_f32 v[212:213], v[208:209], v[212:213], v[208:209]
	v_pk_mul_f32 v[212:213], v[212:213], s[60:61]
	v_pk_mul_f32 v[212:213], v[212:213], s[68:69]
	v_exp_f32_e32 v214, v212
	v_exp_f32_e32 v215, v213
	s_nop 0
	v_pk_add_f32 v[214:215], v[214:215], s[82:83]
	v_rcp_f32_e32 v214, v214
	v_rcp_f32_e32 v215, v215
	s_nop 0
	v_pk_mul_f32 v[212:213], v[208:209], v[214:215]
	v_pk_mul_f32 v[212:213], v[210:211], v[212:213]
	v_cvt_pk_bf16_f32 v216, v212, v213
	global_store_dword v2, v216, s[66:67]
	s_add_u32 s66, s66, 0x2c00
	s_addc_u32 s67, s67, 0
	s_waitcnt vmcnt(16)
	v_lshlrev_b32_e32 v200, 16, v188
	v_and_b32_e32 v201, 0xffff0000, v188
	v_lshlrev_b32_e32 v202, 16, v189
	v_and_b32_e32 v203, 0xffff0000, v189
	v_pk_fma_f32 v[208:209], v[4:5], v[204:205], v[16:17]
	v_pk_fma_f32 v[210:211], v[6:7], v[206:207], v[18:19]
	v_pk_fma_f32 v[208:209], v[8:9], v[196:197], v[208:209]
	v_pk_fma_f32 v[210:211], v[10:11], v[198:199], v[210:211]
	v_pk_fma_f32 v[208:209], v[12:13], v[200:201], v[208:209]
	v_pk_fma_f32 v[210:211], v[14:15], v[202:203], v[210:211]
	v_pk_mul_f32 v[212:213], v[208:209], s[58:59]
	v_pk_mul_f32 v[212:213], v[208:209], v[212:213]
	v_pk_fma_f32 v[212:213], v[208:209], v[212:213], v[208:209]
	v_pk_mul_f32 v[212:213], v[212:213], s[60:61]
	v_pk_mul_f32 v[212:213], v[212:213], s[68:69]
	v_exp_f32_e32 v214, v212
	v_exp_f32_e32 v215, v213
	s_nop 0
	v_pk_add_f32 v[214:215], v[214:215], s[82:83]
	v_rcp_f32_e32 v214, v214
	v_rcp_f32_e32 v215, v215
	s_nop 0
	v_pk_mul_f32 v[212:213], v[208:209], v[214:215]
	v_pk_mul_f32 v[212:213], v[210:211], v[212:213]
	v_cvt_pk_bf16_f32 v216, v212, v213
	global_store_dword v2, v216, s[66:67]
	s_add_u32 s66, s66, 0x2c00
	s_addc_u32 s67, s67, 0
	s_waitcnt vmcnt(15)
	v_lshlrev_b32_e32 v204, 16, v190
	v_and_b32_e32 v205, 0xffff0000, v190
	v_lshlrev_b32_e32 v206, 16, v191
	v_and_b32_e32 v207, 0xffff0000, v191
	v_pk_fma_f32 v[208:209], v[4:5], v[196:197], v[16:17]
	v_pk_fma_f32 v[210:211], v[6:7], v[198:199], v[18:19]
	v_pk_fma_f32 v[208:209], v[8:9], v[200:201], v[208:209]
	v_pk_fma_f32 v[210:211], v[10:11], v[202:203], v[210:211]
	v_pk_fma_f32 v[208:209], v[12:13], v[204:205], v[208:209]
	v_pk_fma_f32 v[210:211], v[14:15], v[206:207], v[210:211]
	v_pk_mul_f32 v[212:213], v[208:209], s[58:59]
	v_pk_mul_f32 v[212:213], v[208:209], v[212:213]
	v_pk_fma_f32 v[212:213], v[208:209], v[212:213], v[208:209]
	v_pk_mul_f32 v[212:213], v[212:213], s[60:61]
	v_pk_mul_f32 v[212:213], v[212:213], s[68:69]
	v_exp_f32_e32 v214, v212
	v_exp_f32_e32 v215, v213
	s_nop 0
	v_pk_add_f32 v[214:215], v[214:215], s[82:83]
	v_rcp_f32_e32 v214, v214
	v_rcp_f32_e32 v215, v215
	s_nop 0
	v_pk_mul_f32 v[212:213], v[208:209], v[214:215]
	v_pk_mul_f32 v[212:213], v[210:211], v[212:213]
	v_cvt_pk_bf16_f32 v216, v212, v213
	global_store_dword v2, v216, s[66:67]
	s_add_u32 s66, s66, 0x2c00
	s_addc_u32 s67, s67, 0
	global_load_dword v160, v2, s[64:65]
	global_load_dword v161, v3, s[64:65]
	s_add_u32 s64, s64, 0x2c00
	s_addc_u32 s65, s65, 0
	global_load_dword v162, v2, s[64:65]
	global_load_dword v163, v3, s[64:65]
	s_add_u32 s64, s64, 0x2c00
	s_addc_u32 s65, s65, 0
	global_load_dword v164, v2, s[64:65]
	global_load_dword v165, v3, s[64:65]
	s_add_u32 s64, s64, 0x2c00
	s_addc_u32 s65, s65, 0
	global_load_dword v166, v2, s[64:65]
	global_load_dword v167, v3, s[64:65]
	s_add_u32 s64, s64, 0x2c00
	s_addc_u32 s65, s65, 0
	global_load_dword v168, v2, s[64:65]
	global_load_dword v169, v3, s[64:65]
	s_add_u32 s64, s64, 0x2c00
	s_addc_u32 s65, s65, 0
	global_load_dword v170, v2, s[64:65]
	global_load_dword v171, v3, s[64:65]
	s_add_u32 s64, s64, 0x2c00
	s_addc_u32 s65, s65, 0
	global_load_dword v172, v2, s[64:65]
	global_load_dword v173, v3, s[64:65]
	s_add_u32 s64, s64, 0x2c00
	s_addc_u32 s65, s65, 0
	global_load_dword v174, v2, s[64:65]
	global_load_dword v175, v3, s[64:65]
	s_add_u32 s64, s64, 0x2c00
	s_addc_u32 s65, s65, 0
	global_load_dword v176, v2, s[64:65]
	global_load_dword v177, v3, s[64:65]
	s_add_u32 s64, s64, 0x2c00
	s_addc_u32 s65, s65, 0
	global_load_dword v178, v2, s[64:65]
	global_load_dword v179, v3, s[64:65]
	s_add_u32 s64, s64, 0x2c00
	s_addc_u32 s65, s65, 0
	global_load_dword v180, v2, s[64:65]
	global_load_dword v181, v3, s[64:65]
	s_add_u32 s64, s64, 0x2c00
	s_addc_u32 s65, s65, 0
	global_load_dword v182, v2, s[64:65]
	global_load_dword v183, v3, s[64:65]
	s_add_u32 s64, s64, 0x2c00
	s_addc_u32 s65, s65, 0
	global_load_dword v184, v2, s[64:65]
	global_load_dword v185, v3, s[64:65]
	s_add_u32 s64, s64, 0x2c00
	s_addc_u32 s65, s65, 0
	global_load_dword v186, v2, s[64:65]
	global_load_dword v187, v3, s[64:65]
	s_add_u32 s64, s64, 0x2c00
	s_addc_u32 s65, s65, 0
	global_load_dword v188, v2, s[64:65]
	global_load_dword v189, v3, s[64:65]
	s_add_u32 s64, s64, 0x2c00
	s_addc_u32 s65, s65, 0
	global_load_dword v190, v2, s[64:65]
	global_load_dword v191, v3, s[64:65]
	s_add_u32 s64, s64, 0x2c00
	s_addc_u32 s65, s65, 0
	s_waitcnt vmcnt(30)
; __device__ __forceinline__ float bf2f(unsigned b) { return __uint_as_float(b << 16); }
; __device__ __forceinline__ unsigned pk2(float lo, float hi) { unsigned r; asm("v_cvt_pk_bf16_f32 %0, %1, %2" : "=v"(r) : "v"(lo), "v"(hi)); return r; }
; __device__ __forceinline__ float gelu_t(float x) { return x * __builtin_amdgcn_rcpf(1.f + __expf(-1.5957691216057308f * (x + 0.044715f * x * x * x))); }
; __device__ __forceinline__ void act_item(int item, u16* UP, const u16* HALO, const float* sconv, const float* wconv, const float* bconv, float* out, int lane) {
;     ...
;     for (int tb = 0; tb < 64; tb += 16) {
;         unsigned gw[16], vw[16];
; #pragma unroll
;         for (int t = 0; t < 16; ++t) { const size_t row = (size_t)rb * 64 + tb + t; gw[t] = *(const unsigned*)(UP + row * FF2 + j0); vw[t] = *(const unsigned*)(UP + row * FF2 + FF + j0); }
; #pragma unroll
;         for (int t = 0; t < 16; ++t) {
;             const int row = rb * 64 + tb + t;
;             if (sample && (t & 3) == 0) { const int ns = (row - TP) >> 2; const float* s0 = sconv + (size_t)ns * 2 * FF2;
;                 const f32x2 a = *(const f32x2*)(s0 + j0), b = *(const f32x2*)(s0 + FF + j0), c = *(const f32x2*)(s0 + FF2 + j0), dd = *(const f32x2*)(s0 + FF2 + FF + j0);
;                 g2[0] = a.x; g2[1] = a.y; v2[0] = b.x; v2[1] = b.y; g1[0] = c.x; g1[1] = c.y; v1[0] = dd.x; v1[1] = dd.y; }
;             const float g0[2] = {bf2f(gw[t] & 0xffffu), bf2f(gw[t] >> 16)}, v0[2] = {bf2f(vw[t] & 0xffffu), bf2f(vw[t] >> 16)};
;             float res[2];
; #pragma unroll
;             for (int p = 0; p < 2; ++p) { const float cgv = bg[p] + wgt[0][p] * g2[p] + wgt[1][p] * g1[p] + wgt[2][p] * g0[p];
;                 const float cvv = bv[p] + wvl[0][p] * v2[p] + wvl[1][p] * v1[p] + wvl[2][p] * v0[p]; res[p] = gelu_t(cgv) * cvv;
;                 g2[p] = g1[p]; g1[p] = g0[p]; v2[p] = v1[p]; v1[p] = v0[p]; }
;             *(unsigned*)(UP + (size_t)row * FF2 + j0) = pk2(res[0], res[1]);
	v_lshlrev_b32_e32 v196, 16, v160
	v_and_b32_e32 v197, 0xffff0000, v160
	v_lshlrev_b32_e32 v198, 16, v161
	v_and_b32_e32 v199, 0xffff0000, v161
	v_pk_fma_f32 v[208:209], v[4:5], v[200:201], v[16:17]
	v_pk_fma_f32 v[210:211], v[6:7], v[202:203], v[18:19]
	v_pk_fma_f32 v[208:209], v[8:9], v[204:205], v[208:209]
	v_pk_fma_f32 v[210:211], v[10:11], v[206:207], v[210:211]
	v_pk_fma_f32 v[208:209], v[12:13], v[196:197], v[208:209]
	v_pk_fma_f32 v[210:211], v[14:15], v[198:199], v[210:211]
	v_pk_mul_f32 v[212:213], v[208:209], s[58:59]
	v_pk_mul_f32 v[212:213], v[208:209], v[212:213]
	v_pk_fma_f32 v[212:213], v[208:209], v[212:213], v[208:209]
	v_pk_mul_f32 v[212:213], v[212:213], s[60:61]
	v_pk_mul_f32 v[212:213], v[212:213], s[68:69]
	v_exp_f32_e32 v214, v212
	v_exp_f32_e32 v215, v213
	s_nop 0
	v_pk_add_f32 v[214:215], v[214:215], s[82:83]
	v_rcp_f32_e32 v214, v214
	v_rcp_f32_e32 v215, v215
	s_nop 0
	v_pk_mul_f32 v[212:213], v[208:209], v[214:215]
	v_pk_mul_f32 v[212:213], v[210:211], v[212:213]
	v_cvt_pk_bf16_f32 v216, v212, v213
	global_store_dword v2, v216, s[66:67]
	s_add_u32 s66, s66, 0x2c00
	s_addc_u32 s67, s67, 0
	s_waitcnt vmcnt(29)
	v_lshlrev_b32_e32 v200, 16, v162
	v_and_b32_e32 v201, 0xffff0000, v162
	v_lshlrev_b32_e32 v202, 16, v163
	v_and_b32_e32 v203, 0xffff0000, v163
	v_pk_fma_f32 v[208:209], v[4:5], v[204:205], v[16:17]
	v_pk_fma_f32 v[210:211], v[6:7], v[206:207], v[18:19]
	v_pk_fma_f32 v[208:209], v[8:9], v[196:197], v[208:209]
	v_pk_fma_f32 v[210:211], v[10:11], v[198:199], v[210:211]
	v_pk_fma_f32 v[208:209], v[12:13], v[200:201], v[208:209]
	v_pk_fma_f32 v[210:211], v[14:15], v[202:203], v[210:211]
	v_pk_mul_f32 v[212:213], v[208:209], s[58:59]
	v_pk_mul_f32 v[212:213], v[208:209], v[212:213]
	v_pk_fma_f32 v[212:213], v[208:209], v[212:213], v[208:209]
	v_pk_mul_f32 v[212:213], v[212:213], s[60:61]
	v_pk_mul_f32 v[212:213], v[212:213], s[68:69]
	v_exp_f32_e32 v214, v212
	v_exp_f32_e32 v215, v213
	s_nop 0
	v_pk_add_f32 v[214:215], v[214:215], s[82:83]
	v_rcp_f32_e32 v214, v214
	v_rcp_f32_e32 v215, v215
	s_nop 0
	v_pk_mul_f32 v[212:213], v[208:209], v[214:215]
	v_pk_mul_f32 v[212:213], v[210:211], v[212:213]
	v_cvt_pk_bf16_f32 v216, v212, v213
	global_store_dword v2, v216, s[66:67]
	s_add_u32 s66, s66, 0x2c00
	s_addc_u32 s67, s67, 0
	s_waitcnt vmcnt(28)
	v_lshlrev_b32_e32 v204, 16, v164
	v_and_b32_e32 v205, 0xffff0000, v164
	v_lshlrev_b32_e32 v206, 16, v165
	v_and_b32_e32 v207, 0xffff0000, v165
	v_pk_fma_f32 v[208:209], v[4:5], v[196:197], v[16:17]
	v_pk_fma_f32 v[210:211], v[6:7], v[198:199], v[18:19]
	v_pk_fma_f32 v[208:209], v[8:9], v[200:201], v[208:209]
	v_pk_fma_f32 v[210:211], v[10:11], v[202:203], v[210:211]
	v_pk_fma_f32 v[208:209], v[12:13], v[204:205], v[208:209]
	v_pk_fma_f32 v[210:211], v[14:15], v[206:207], v[210:211]
	v_pk_mul_f32 v[212:213], v[208:209], s[58:59]
	v_pk_mul_f32 v[212:213], v[208:209], v[212:213]
	v_pk_fma_f32 v[212:213], v[208:209], v[212:213], v[208:209]
	v_pk_mul_f32 v[212:213], v[212:213], s[60:61]
	v_pk_mul_f32 v[212:213], v[212:213], s[68:69]
	v_exp_f32_e32 v214, v212
	v_exp_f32_e32 v215, v213
	s_nop 0
	v_pk_add_f32 v[214:215], v[214:215], s[82:83]
	v_rcp_f32_e32 v214, v214
	v_rcp_f32_e32 v215, v215
	s_nop 0
	v_pk_mul_f32 v[212:213], v[208:209], v[214:215]
	v_pk_mul_f32 v[212:213], v[210:211], v[212:213]
	v_cvt_pk_bf16_f32 v216, v212, v213
	global_store_dword v2, v216, s[66:67]
	s_add_u32 s66, s66, 0x2c00
	s_addc_u32 s67, s67, 0
	s_waitcnt vmcnt(27)
	v_lshlrev_b32_e32 v196, 16, v166
	v_and_b32_e32 v197, 0xffff0000, v166
	v_lshlrev_b32_e32 v198, 16, v167
	v_and_b32_e32 v199, 0xffff0000, v167
	v_pk_fma_f32 v[208:209], v[4:5], v[200:201], v[16:17]
	v_pk_fma_f32 v[210:211], v[6:7], v[202:203], v[18:19]
	v_pk_fma_f32 v[208:209], v[8:9], v[204:205], v[208:209]
	v_pk_fma_f32 v[210:211], v[10:11], v[206:207], v[210:211]
	v_pk_fma_f32 v[208:209], v[12:13], v[196:197], v[208:209]
	v_pk_fma_f32 v[210:211], v[14:15], v[198:199], v[210:211]
	v_pk_mul_f32 v[212:213], v[208:209], s[58:59]
	v_pk_mul_f32 v[212:213], v[208:209], v[212:213]
	v_pk_fma_f32 v[212:213], v[208:209], v[212:213], v[208:209]
	v_pk_mul_f32 v[212:213], v[212:213], s[60:61]
	v_pk_mul_f32 v[212:213], v[212:213], s[68:69]
	v_exp_f32_e32 v214, v212
	v_exp_f32_e32 v215, v213
	s_nop 0
	v_pk_add_f32 v[214:215], v[214:215], s[82:83]
	v_rcp_f32_e32 v214, v214
	v_rcp_f32_e32 v215, v215
	s_nop 0
	v_pk_mul_f32 v[212:213], v[208:209], v[214:215]
	v_pk_mul_f32 v[212:213], v[210:211], v[212:213]
	v_cvt_pk_bf16_f32 v216, v212, v213
	global_store_dword v2, v216, s[66:67]
	s_add_u32 s66, s66, 0x2c00
	s_addc_u32 s67, s67, 0
	s_waitcnt vmcnt(26)
	v_lshlrev_b32_e32 v200, 16, v168
	v_and_b32_e32 v201, 0xffff0000, v168
	v_lshlrev_b32_e32 v202, 16, v169
	v_and_b32_e32 v203, 0xffff0000, v169
	v_pk_fma_f32 v[208:209], v[4:5], v[204:205], v[16:17]
	v_pk_fma_f32 v[210:211], v[6:7], v[206:207], v[18:19]
	v_pk_fma_f32 v[208:209], v[8:9], v[196:197], v[208:209]
	v_pk_fma_f32 v[210:211], v[10:11], v[198:199], v[210:211]
	v_pk_fma_f32 v[208:209], v[12:13], v[200:201], v[208:209]
	v_pk_fma_f32 v[210:211], v[14:15], v[202:203], v[210:211]
	v_pk_mul_f32 v[212:213], v[208:209], s[58:59]
	v_pk_mul_f32 v[212:213], v[208:209], v[212:213]
	v_pk_fma_f32 v[212:213], v[208:209], v[212:213], v[208:209]
	v_pk_mul_f32 v[212:213], v[212:213], s[60:61]
	v_pk_mul_f32 v[212:213], v[212:213], s[68:69]
	v_exp_f32_e32 v214, v212
	v_exp_f32_e32 v215, v213
	s_nop 0
	v_pk_add_f32 v[214:215], v[214:215], s[82:83]
	v_rcp_f32_e32 v214, v214
	v_rcp_f32_e32 v215, v215
	s_nop 0
	v_pk_mul_f32 v[212:213], v[208:209], v[214:215]
	v_pk_mul_f32 v[212:213], v[210:211], v[212:213]
	v_cvt_pk_bf16_f32 v216, v212, v213
	global_store_dword v2, v216, s[66:67]
	s_add_u32 s66, s66, 0x2c00
	s_addc_u32 s67, s67, 0
	s_waitcnt vmcnt(25)
; __device__ __forceinline__ float bf2f(unsigned b) { return __uint_as_float(b << 16); }
; __device__ __forceinline__ unsigned pk2(float lo, float hi) { unsigned r; asm("v_cvt_pk_bf16_f32 %0, %1, %2" : "=v"(r) : "v"(lo), "v"(hi)); return r; }
; __device__ __forceinline__ float gelu_t(float x) { return x * __builtin_amdgcn_rcpf(1.f + __expf(-1.5957691216057308f * (x + 0.044715f * x * x * x))); }
; __device__ __forceinline__ void act_item(int item, u16* UP, const u16* HALO, const float* sconv, const float* wconv, const float* bconv, float* out, int lane) {
;     ...
;     for (int tb = 0; tb < 64; tb += 16) {
;         unsigned gw[16], vw[16];
; #pragma unroll
;         for (int t = 0; t < 16; ++t) { const size_t row = (size_t)rb * 64 + tb + t; gw[t] = *(const unsigned*)(UP + row * FF2 + j0); vw[t] = *(const unsigned*)(UP + row * FF2 + FF + j0); }
; #pragma unroll
;         for (int t = 0; t < 16; ++t) {
;             const int row = rb * 64 + tb + t;
;             if (sample && (t & 3) == 0) { const int ns = (row - TP) >> 2; const float* s0 = sconv + (size_t)ns * 2 * FF2;
;                 const f32x2 a = *(const f32x2*)(s0 + j0), b = *(const f32x2*)(s0 + FF + j0), c = *(const f32x2*)(s0 + FF2 + j0), dd = *(const f32x2*)(s0 + FF2 + FF + j0);
;                 g2[0] = a.x; g2[1] = a.y; v2[0] = b.x; v2[1] = b.y; g1[0] = c.x; g1[1] = c.y; v1[0] = dd.x; v1[1] = dd.y; }
;             const float g0[2] = {bf2f(gw[t] & 0xffffu), bf2f(gw[t] >> 16)}, v0[2] = {bf2f(vw[t] & 0xffffu), bf2f(vw[t] >> 16)};
;             float res[2];
; #pragma unroll
;             for (int p = 0; p < 2; ++p) { const float cgv = bg[p] + wgt[0][p] * g2[p] + wgt[1][p] * g1[p] + wgt[2][p] * g0[p];
;                 const float cvv = bv[p] + wvl[0][p] * v2[p] + wvl[1][p] * v1[p] + wvl[2][p] * v0[p]; res[p] = gelu_t(cgv) * cvv;
;                 g2[p] = g1[p]; g1[p] = g0[p]; v2[p] = v1[p]; v1[p] = v0[p]; }
;             *(unsigned*)(UP + (size_t)row * FF2 + j0) = pk2(res[0], res[1]);
	v_lshlrev_b32_e32 v204, 16, v170
	v_and_b32_e32 v205, 0xffff0000, v170
	v_lshlrev_b32_e32 v206, 16, v171
	v_and_b32_e32 v207, 0xffff0000, v171
	v_pk_fma_f32 v[208:209], v[4:5], v[196:197], v[16:17]
	v_pk_fma_f32 v[210:211], v[6:7], v[198:199], v[18:19]
	v_pk_fma_f32 v[208:209], v[8:9], v[200:201], v[208:209]
	v_pk_fma_f32 v[210:211], v[10:11], v[202:203], v[210:211]
	v_pk_fma_f32 v[208:209], v[12:13], v[204:205], v[208:209]
	v_pk_fma_f32 v[210:211], v[14:15], v[206:207], v[210:211]
	v_pk_mul_f32 v[212:213], v[208:209], s[58:59]
	v_pk_mul_f32 v[212:213], v[208:209], v[212:213]
	v_pk_fma_f32 v[212:213], v[208:209], v[212:213], v[208:209]
	v_pk_mul_f32 v[212:213], v[212:213], s[60:61]
	v_pk_mul_f32 v[212:213], v[212:213], s[68:69]
	v_exp_f32_e32 v214, v212
	v_exp_f32_e32 v215, v213
	s_nop 0
	v_pk_add_f32 v[214:215], v[214:215], s[82:83]
	v_rcp_f32_e32 v214, v214
	v_rcp_f32_e32 v215, v215
	s_nop 0
	v_pk_mul_f32 v[212:213], v[208:209], v[214:215]
	v_pk_mul_f32 v[212:213], v[210:211], v[212:213]
	v_cvt_pk_bf16_f32 v216, v212, v213
	global_store_dword v2, v216, s[66:67]
	s_add_u32 s66, s66, 0x2c00
	s_addc_u32 s67, s67, 0
	s_waitcnt vmcnt(24)
	v_lshlrev_b32_e32 v196, 16, v172
	v_and_b32_e32 v197, 0xffff0000, v172
	v_lshlrev_b32_e32 v198, 16, v173
	v_and_b32_e32 v199, 0xffff0000, v173
	v_pk_fma_f32 v[208:209], v[4:5], v[200:201], v[16:17]
	v_pk_fma_f32 v[210:211], v[6:7], v[202:203], v[18:19]
	v_pk_fma_f32 v[208:209], v[8:9], v[204:205], v[208:209]
	v_pk_fma_f32 v[210:211], v[10:11], v[206:207], v[210:211]
	v_pk_fma_f32 v[208:209], v[12:13], v[196:197], v[208:209]
	v_pk_fma_f32 v[210:211], v[14:15], v[198:199], v[210:211]
	v_pk_mul_f32 v[212:213], v[208:209], s[58:59]
	v_pk_mul_f32 v[212:213], v[208:209], v[212:213]
	v_pk_fma_f32 v[212:213], v[208:209], v[212:213], v[208:209]
	v_pk_mul_f32 v[212:213], v[212:213], s[60:61]
	v_pk_mul_f32 v[212:213], v[212:213], s[68:69]
	v_exp_f32_e32 v214, v212
	v_exp_f32_e32 v215, v213
	s_nop 0
	v_pk_add_f32 v[214:215], v[214:215], s[82:83]
	v_rcp_f32_e32 v214, v214
	v_rcp_f32_e32 v215, v215
	s_nop 0
	v_pk_mul_f32 v[212:213], v[208:209], v[214:215]
	v_pk_mul_f32 v[212:213], v[210:211], v[212:213]
	v_cvt_pk_bf16_f32 v216, v212, v213
	global_store_dword v2, v216, s[66:67]
	s_add_u32 s66, s66, 0x2c00
	s_addc_u32 s67, s67, 0
	s_waitcnt vmcnt(23)
	v_lshlrev_b32_e32 v200, 16, v174
	v_and_b32_e32 v201, 0xffff0000, v174
	v_lshlrev_b32_e32 v202, 16, v175
	v_and_b32_e32 v203, 0xffff0000, v175
	v_pk_fma_f32 v[208:209], v[4:5], v[204:205], v[16:17]
	v_pk_fma_f32 v[210:211], v[6:7], v[206:207], v[18:19]
	v_pk_fma_f32 v[208:209], v[8:9], v[196:197], v[208:209]
	v_pk_fma_f32 v[210:211], v[10:11], v[198:199], v[210:211]
	v_pk_fma_f32 v[208:209], v[12:13], v[200:201], v[208:209]
	v_pk_fma_f32 v[210:211], v[14:15], v[202:203], v[210:211]
	v_pk_mul_f32 v[212:213], v[208:209], s[58:59]
	v_pk_mul_f32 v[212:213], v[208:209], v[212:213]
	v_pk_fma_f32 v[212:213], v[208:209], v[212:213], v[208:209]
	v_pk_mul_f32 v[212:213], v[212:213], s[60:61]
	v_pk_mul_f32 v[212:213], v[212:213], s[68:69]
	v_exp_f32_e32 v214, v212
	v_exp_f32_e32 v215, v213
	s_nop 0
	v_pk_add_f32 v[214:215], v[214:215], s[82:83]
	v_rcp_f32_e32 v214, v214
	v_rcp_f32_e32 v215, v215
	s_nop 0
	v_pk_mul_f32 v[212:213], v[208:209], v[214:215]
	v_pk_mul_f32 v[212:213], v[210:211], v[212:213]
	v_cvt_pk_bf16_f32 v216, v212, v213
	global_store_dword v2, v216, s[66:67]
	s_add_u32 s66, s66, 0x2c00
	s_addc_u32 s67, s67, 0
	s_waitcnt vmcnt(22)
	v_lshlrev_b32_e32 v204, 16, v176
	v_and_b32_e32 v205, 0xffff0000, v176
	v_lshlrev_b32_e32 v206, 16, v177
	v_and_b32_e32 v207, 0xffff0000, v177
	v_pk_fma_f32 v[208:209], v[4:5], v[196:197], v[16:17]
	v_pk_fma_f32 v[210:211], v[6:7], v[198:199], v[18:19]
	v_pk_fma_f32 v[208:209], v[8:9], v[200:201], v[208:209]
	v_pk_fma_f32 v[210:211], v[10:11], v[202:203], v[210:211]
	v_pk_fma_f32 v[208:209], v[12:13], v[204:205], v[208:209]
	v_pk_fma_f32 v[210:211], v[14:15], v[206:207], v[210:211]
	v_pk_mul_f32 v[212:213], v[208:209], s[58:59]
	v_pk_mul_f32 v[212:213], v[208:209], v[212:213]
	v_pk_fma_f32 v[212:213], v[208:209], v[212:213], v[208:209]
	v_pk_mul_f32 v[212:213], v[212:213], s[60:61]
	v_pk_mul_f32 v[212:213], v[212:213], s[68:69]
	v_exp_f32_e32 v214, v212
	v_exp_f32_e32 v215, v213
	s_nop 0
	v_pk_add_f32 v[214:215], v[214:215], s[82:83]
	v_rcp_f32_e32 v214, v214
	v_rcp_f32_e32 v215, v215
	s_nop 0
	v_pk_mul_f32 v[212:213], v[208:209], v[214:215]
	v_pk_mul_f32 v[212:213], v[210:211], v[212:213]
	v_cvt_pk_bf16_f32 v216, v212, v213
	global_store_dword v2, v216, s[66:67]
	s_add_u32 s66, s66, 0x2c00
	s_addc_u32 s67, s67, 0
	s_waitcnt vmcnt(21)
	v_lshlrev_b32_e32 v196, 16, v178
	v_and_b32_e32 v197, 0xffff0000, v178
	v_lshlrev_b32_e32 v198, 16, v179
	v_and_b32_e32 v199, 0xffff0000, v179
	v_pk_fma_f32 v[208:209], v[4:5], v[200:201], v[16:17]
	v_pk_fma_f32 v[210:211], v[6:7], v[202:203], v[18:19]
	v_pk_fma_f32 v[208:209], v[8:9], v[204:205], v[208:209]
	v_pk_fma_f32 v[210:211], v[10:11], v[206:207], v[210:211]
	v_pk_fma_f32 v[208:209], v[12:13], v[196:197], v[208:209]
	v_pk_fma_f32 v[210:211], v[14:15], v[198:199], v[210:211]
	v_pk_mul_f32 v[212:213], v[208:209], s[58:59]
	v_pk_mul_f32 v[212:213], v[208:209], v[212:213]
	v_pk_fma_f32 v[212:213], v[208:209], v[212:213], v[208:209]
	v_pk_mul_f32 v[212:213], v[212:213], s[60:61]
	v_pk_mul_f32 v[212:213], v[212:213], s[68:69]
	v_exp_f32_e32 v214, v212
	v_exp_f32_e32 v215, v213
	s_nop 0
	v_pk_add_f32 v[214:215], v[214:215], s[82:83]
	v_rcp_f32_e32 v214, v214
	v_rcp_f32_e32 v215, v215
	s_nop 0
	v_pk_mul_f32 v[212:213], v[208:209], v[214:215]
	v_pk_mul_f32 v[212:213], v[210:211], v[212:213]
	v_cvt_pk_bf16_f32 v216, v212, v213
	global_store_dword v2, v216, s[66:67]
	s_add_u32 s66, s66, 0x2c00
	s_addc_u32 s67, s67, 0
	s_waitcnt vmcnt(20)
; __device__ __forceinline__ float bf2f(unsigned b) { return __uint_as_float(b << 16); }
; __device__ __forceinline__ unsigned pk2(float lo, float hi) { unsigned r; asm("v_cvt_pk_bf16_f32 %0, %1, %2" : "=v"(r) : "v"(lo), "v"(hi)); return r; }
; __device__ __forceinline__ float gelu_t(float x) { return x * __builtin_amdgcn_rcpf(1.f + __expf(-1.5957691216057308f * (x + 0.044715f * x * x * x))); }
; __device__ __forceinline__ void act_item(int item, u16* UP, const u16* HALO, const float* sconv, const float* wconv, const float* bconv, float* out, int lane) {
;     ...
;     for (int tb = 0; tb < 64; tb += 16) {
;         unsigned gw[16], vw[16];
; #pragma unroll
;         for (int t = 0; t < 16; ++t) { const size_t row = (size_t)rb * 64 + tb + t; gw[t] = *(const unsigned*)(UP + row * FF2 + j0); vw[t] = *(const unsigned*)(UP + row * FF2 + FF + j0); }
; #pragma unroll
;         for (int t = 0; t < 16; ++t) {
;             const int row = rb * 64 + tb + t;
;             if (sample && (t & 3) == 0) { const int ns = (row - TP) >> 2; const float* s0 = sconv + (size_t)ns * 2 * FF2;
;                 const f32x2 a = *(const f32x2*)(s0 + j0), b = *(const f32x2*)(s0 + FF + j0), c = *(const f32x2*)(s0 + FF2 + j0), dd = *(const f32x2*)(s0 + FF2 + FF + j0);
;                 g2[0] = a.x; g2[1] = a.y; v2[0] = b.x; v2[1] = b.y; g1[0] = c.x; g1[1] = c.y; v1[0] = dd.x; v1[1] = dd.y; }
;             const float g0[2] = {bf2f(gw[t] & 0xffffu), bf2f(gw[t] >> 16)}, v0[2] = {bf2f(vw[t] & 0xffffu), bf2f(vw[t] >> 16)};
;             float res[2];
; #pragma unroll
;             for (int p = 0; p < 2; ++p) { const float cgv = bg[p] + wgt[0][p] * g2[p] + wgt[1][p] * g1[p] + wgt[2][p] * g0[p];
;                 const float cvv = bv[p] + wvl[0][p] * v2[p] + wvl[1][p] * v1[p] + wvl[2][p] * v0[p]; res[p] = gelu_t(cgv) * cvv;
;                 g2[p] = g1[p]; g1[p] = g0[p]; v2[p] = v1[p]; v1[p] = v0[p]; }
;             *(unsigned*)(UP + (size_t)row * FF2 + j0) = pk2(res[0], res[1]);
;             if (!sample) { const int tq = row & 2047; if (tq >= 2046) { float* o = out + O_CONVP + ((size_t)(row >> 11) * 2 + (tq - 2046)) * FF2;
;                     *(f32x2*)(o + j0) = (f32x2){g0[0], g0[1]}; *(f32x2*)(o + FF + j0) = (f32x2){v0[0], v0[1]}; } }
	v_lshlrev_b32_e32 v200, 16, v180
	v_and_b32_e32 v201, 0xffff0000, v180
	v_lshlrev_b32_e32 v202, 16, v181
	v_and_b32_e32 v203, 0xffff0000, v181
	v_pk_fma_f32 v[208:209], v[4:5], v[204:205], v[16:17]
	v_pk_fma_f32 v[210:211], v[6:7], v[206:207], v[18:19]
	v_pk_fma_f32 v[208:209], v[8:9], v[196:197], v[208:209]
	v_pk_fma_f32 v[210:211], v[10:11], v[198:199], v[210:211]
	v_pk_fma_f32 v[208:209], v[12:13], v[200:201], v[208:209]
	v_pk_fma_f32 v[210:211], v[14:15], v[202:203], v[210:211]
	v_pk_mul_f32 v[212:213], v[208:209], s[58:59]
	v_pk_mul_f32 v[212:213], v[208:209], v[212:213]
	v_pk_fma_f32 v[212:213], v[208:209], v[212:213], v[208:209]
	v_pk_mul_f32 v[212:213], v[212:213], s[60:61]
	v_pk_mul_f32 v[212:213], v[212:213], s[68:69]
	v_exp_f32_e32 v214, v212
	v_exp_f32_e32 v215, v213
	s_nop 0
	v_pk_add_f32 v[214:215], v[214:215], s[82:83]
	v_rcp_f32_e32 v214, v214
	v_rcp_f32_e32 v215, v215
	s_nop 0
	v_pk_mul_f32 v[212:213], v[208:209], v[214:215]
	v_pk_mul_f32 v[212:213], v[210:211], v[212:213]
	v_cvt_pk_bf16_f32 v216, v212, v213
	global_store_dword v2, v216, s[66:67]
	s_add_u32 s66, s66, 0x2c00
	s_addc_u32 s67, s67, 0
	s_waitcnt vmcnt(19)
	v_lshlrev_b32_e32 v204, 16, v182
	v_and_b32_e32 v205, 0xffff0000, v182
	v_lshlrev_b32_e32 v206, 16, v183
	v_and_b32_e32 v207, 0xffff0000, v183
	v_pk_fma_f32 v[208:209], v[4:5], v[196:197], v[16:17]
	v_pk_fma_f32 v[210:211], v[6:7], v[198:199], v[18:19]
	v_pk_fma_f32 v[208:209], v[8:9], v[200:201], v[208:209]
	v_pk_fma_f32 v[210:211], v[10:11], v[202:203], v[210:211]
	v_pk_fma_f32 v[208:209], v[12:13], v[204:205], v[208:209]
	v_pk_fma_f32 v[210:211], v[14:15], v[206:207], v[210:211]
	v_pk_mul_f32 v[212:213], v[208:209], s[58:59]
	v_pk_mul_f32 v[212:213], v[208:209], v[212:213]
	v_pk_fma_f32 v[212:213], v[208:209], v[212:213], v[208:209]
	v_pk_mul_f32 v[212:213], v[212:213], s[60:61]
	v_pk_mul_f32 v[212:213], v[212:213], s[68:69]
	v_exp_f32_e32 v214, v212
	v_exp_f32_e32 v215, v213
	s_nop 0
	v_pk_add_f32 v[214:215], v[214:215], s[82:83]
	v_rcp_f32_e32 v214, v214
	v_rcp_f32_e32 v215, v215
	s_nop 0
	v_pk_mul_f32 v[212:213], v[208:209], v[214:215]
	v_pk_mul_f32 v[212:213], v[210:211], v[212:213]
	v_cvt_pk_bf16_f32 v216, v212, v213
	global_store_dword v2, v216, s[66:67]
	s_add_u32 s66, s66, 0x2c00
	s_addc_u32 s67, s67, 0
	s_waitcnt vmcnt(18)
	v_lshlrev_b32_e32 v196, 16, v184
	v_and_b32_e32 v197, 0xffff0000, v184
	v_lshlrev_b32_e32 v198, 16, v185
	v_and_b32_e32 v199, 0xffff0000, v185
	v_pk_fma_f32 v[208:209], v[4:5], v[200:201], v[16:17]
	v_pk_fma_f32 v[210:211], v[6:7], v[202:203], v[18:19]
	v_pk_fma_f32 v[208:209], v[8:9], v[204:205], v[208:209]
	v_pk_fma_f32 v[210:211], v[10:11], v[206:207], v[210:211]
	v_pk_fma_f32 v[208:209], v[12:13], v[196:197], v[208:209]
	v_pk_fma_f32 v[210:211], v[14:15], v[198:199], v[210:211]
	v_pk_mul_f32 v[212:213], v[208:209], s[58:59]
	v_pk_mul_f32 v[212:213], v[208:209], v[212:213]
	v_pk_fma_f32 v[212:213], v[208:209], v[212:213], v[208:209]
	v_pk_mul_f32 v[212:213], v[212:213], s[60:61]
	v_pk_mul_f32 v[212:213], v[212:213], s[68:69]
	v_exp_f32_e32 v214, v212
	v_exp_f32_e32 v215, v213
	s_nop 0
	v_pk_add_f32 v[214:215], v[214:215], s[82:83]
	v_rcp_f32_e32 v214, v214
	v_rcp_f32_e32 v215, v215
	s_nop 0
	v_pk_mul_f32 v[212:213], v[208:209], v[214:215]
	v_pk_mul_f32 v[212:213], v[210:211], v[212:213]
	v_cvt_pk_bf16_f32 v216, v212, v213
	global_store_dword v2, v216, s[66:67]
	s_add_u32 s66, s66, 0x2c00
	s_addc_u32 s67, s67, 0
	s_waitcnt vmcnt(17)
	v_lshlrev_b32_e32 v200, 16, v186
	v_and_b32_e32 v201, 0xffff0000, v186
	v_lshlrev_b32_e32 v202, 16, v187
	v_and_b32_e32 v203, 0xffff0000, v187
	v_pk_fma_f32 v[208:209], v[4:5], v[204:205], v[16:17]
	v_pk_fma_f32 v[210:211], v[6:7], v[206:207], v[18:19]
	v_pk_fma_f32 v[208:209], v[8:9], v[196:197], v[208:209]
	v_pk_fma_f32 v[210:211], v[10:11], v[198:199], v[210:211]
	v_pk_fma_f32 v[208:209], v[12:13], v[200:201], v[208:209]
	v_pk_fma_f32 v[210:211], v[14:15], v[202:203], v[210:211]
	v_pk_mul_f32 v[212:213], v[208:209], s[58:59]
	v_pk_mul_f32 v[212:213], v[208:209], v[212:213]
	v_pk_fma_f32 v[212:213], v[208:209], v[212:213], v[208:209]
	v_pk_mul_f32 v[212:213], v[212:213], s[60:61]
	v_pk_mul_f32 v[212:213], v[212:213], s[68:69]
	v_exp_f32_e32 v214, v212
	v_exp_f32_e32 v215, v213
	s_nop 0
	v_pk_add_f32 v[214:215], v[214:215], s[82:83]
	v_rcp_f32_e32 v214, v214
	v_rcp_f32_e32 v215, v215
	s_nop 0
	v_pk_mul_f32 v[212:213], v[208:209], v[214:215]
	v_pk_mul_f32 v[212:213], v[210:211], v[212:213]
	v_cvt_pk_bf16_f32 v216, v212, v213
	global_store_dword v2, v216, s[66:67]
	s_add_u32 s66, s66, 0x2c00
	s_addc_u32 s67, s67, 0
	s_waitcnt vmcnt(16)
	v_lshlrev_b32_e32 v204, 16, v188
	v_and_b32_e32 v205, 0xffff0000, v188
	v_lshlrev_b32_e32 v206, 16, v189
	v_and_b32_e32 v207, 0xffff0000, v189
	v_pk_fma_f32 v[208:209], v[4:5], v[196:197], v[16:17]
	v_pk_fma_f32 v[210:211], v[6:7], v[198:199], v[18:19]
	v_pk_fma_f32 v[208:209], v[8:9], v[200:201], v[208:209]
	v_pk_fma_f32 v[210:211], v[10:11], v[202:203], v[210:211]
	v_pk_fma_f32 v[208:209], v[12:13], v[204:205], v[208:209]
	v_pk_fma_f32 v[210:211], v[14:15], v[206:207], v[210:211]
	v_pk_mul_f32 v[212:213], v[208:209], s[58:59]
	v_pk_mul_f32 v[212:213], v[208:209], v[212:213]
	v_pk_fma_f32 v[212:213], v[208:209], v[212:213], v[208:209]
	v_pk_mul_f32 v[212:213], v[212:213], s[60:61]
	v_pk_mul_f32 v[212:213], v[212:213], s[68:69]
	v_exp_f32_e32 v214, v212
	v_exp_f32_e32 v215, v213
	s_cmp_lg_u32 s1, 31
	s_cbranch_scc1 .Lact_ncs0
	s_lshr_b32 s6, s0, 5
	s_lshl_b32 s6, s6, 1
	s_mul_i32 s6, s6, 0x5800
	s_add_u32 s6, s3, s6
	s_addc_u32 s7, s21, 0
	global_store_dwordx2 v1, v[204:205], s[6:7]
	s_add_u32 s6, s6, 0x2c00
	s_addc_u32 s7, s7, 0
	global_store_dwordx2 v1, v[206:207], s[6:7]
; __device__ __forceinline__ float bf2f(unsigned b) { return __uint_as_float(b << 16); }
; __device__ __forceinline__ unsigned pk2(float lo, float hi) { unsigned r; asm("v_cvt_pk_bf16_f32 %0, %1, %2" : "=v"(r) : "v"(lo), "v"(hi)); return r; }
; __device__ __forceinline__ float gelu_t(float x) { return x * __builtin_amdgcn_rcpf(1.f + __expf(-1.5957691216057308f * (x + 0.044715f * x * x * x))); }
; __device__ __forceinline__ void act_item(int item, u16* UP, const u16* HALO, const float* sconv, const float* wconv, const float* bconv, float* out, int lane) {
;     ...
;         for (int t = 0; t < 16; ++t) {
;             const int row = rb * 64 + tb + t;
;             if (sample && (t & 3) == 0) { const int ns = (row - TP) >> 2; const float* s0 = sconv + (size_t)ns * 2 * FF2;
;                 const f32x2 a = *(const f32x2*)(s0 + j0), b = *(const f32x2*)(s0 + FF + j0), c = *(const f32x2*)(s0 + FF2 + j0), dd = *(const f32x2*)(s0 + FF2 + FF + j0);
;                 g2[0] = a.x; g2[1] = a.y; v2[0] = b.x; v2[1] = b.y; g1[0] = c.x; g1[1] = c.y; v1[0] = dd.x; v1[1] = dd.y; }
;             const float g0[2] = {bf2f(gw[t] & 0xffffu), bf2f(gw[t] >> 16)}, v0[2] = {bf2f(vw[t] & 0xffffu), bf2f(vw[t] >> 16)};
;             float res[2];
; #pragma unroll
;             for (int p = 0; p < 2; ++p) { const float cgv = bg[p] + wgt[0][p] * g2[p] + wgt[1][p] * g1[p] + wgt[2][p] * g0[p];
;                 const float cvv = bv[p] + wvl[0][p] * v2[p] + wvl[1][p] * v1[p] + wvl[2][p] * v0[p]; res[p] = gelu_t(cgv) * cvv;
;                 g2[p] = g1[p]; g1[p] = g0[p]; v2[p] = v1[p]; v1[p] = v0[p]; }
;             *(unsigned*)(UP + (size_t)row * FF2 + j0) = pk2(res[0], res[1]);
;             if (!sample) { const int tq = row & 2047; if (tq >= 2046) { float* o = out + O_CONVP + ((size_t)(row >> 11) * 2 + (tq - 2046)) * FF2;
;                     *(f32x2*)(o + j0) = (f32x2){g0[0], g0[1]}; *(f32x2*)(o + FF + j0) = (f32x2){v0[0], v0[1]}; } }
.Lact_ncs0:
	v_pk_add_f32 v[214:215], v[214:215], s[82:83]
	v_rcp_f32_e32 v214, v214
	v_rcp_f32_e32 v215, v215
	s_nop 0
	v_pk_mul_f32 v[212:213], v[208:209], v[214:215]
	v_pk_mul_f32 v[212:213], v[210:211], v[212:213]
	v_cvt_pk_bf16_f32 v216, v212, v213
	global_store_dword v2, v216, s[66:67]
	s_add_u32 s66, s66, 0x2c00
	s_addc_u32 s67, s67, 0
	s_waitcnt vmcnt(15)
	v_lshlrev_b32_e32 v196, 16, v190
	v_and_b32_e32 v197, 0xffff0000, v190
	v_lshlrev_b32_e32 v198, 16, v191
	v_and_b32_e32 v199, 0xffff0000, v191
	v_pk_fma_f32 v[208:209], v[4:5], v[200:201], v[16:17]
	v_pk_fma_f32 v[210:211], v[6:7], v[202:203], v[18:19]
	v_pk_fma_f32 v[208:209], v[8:9], v[204:205], v[208:209]
	v_pk_fma_f32 v[210:211], v[10:11], v[206:207], v[210:211]
	v_pk_fma_f32 v[208:209], v[12:13], v[196:197], v[208:209]
	v_pk_fma_f32 v[210:211], v[14:15], v[198:199], v[210:211]
	v_pk_mul_f32 v[212:213], v[208:209], s[58:59]
	v_pk_mul_f32 v[212:213], v[208:209], v[212:213]
	v_pk_fma_f32 v[212:213], v[208:209], v[212:213], v[208:209]
	v_pk_mul_f32 v[212:213], v[212:213], s[60:61]
	v_pk_mul_f32 v[212:213], v[212:213], s[68:69]
	v_exp_f32_e32 v214, v212
	v_exp_f32_e32 v215, v213
	s_cmp_lg_u32 s1, 31
	s_cbranch_scc1 .Lact_ncs1
	s_lshr_b32 s6, s0, 5
	s_lshl_b32 s6, s6, 1
	s_add_i32 s6, s6, 1
	s_mul_i32 s6, s6, 0x5800
	s_add_u32 s6, s3, s6
	s_addc_u32 s7, s21, 0
	global_store_dwordx2 v1, v[196:197], s[6:7]
	s_add_u32 s6, s6, 0x2c00
	s_addc_u32 s7, s7, 0
	global_store_dwordx2 v1, v[198:199], s[6:7]
.Lact_ncs1:
	v_pk_add_f32 v[214:215], v[214:215], s[82:83]
	v_rcp_f32_e32 v214, v214
	v_rcp_f32_e32 v215, v215
	s_nop 0
	v_pk_mul_f32 v[212:213], v[208:209], v[214:215]
	v_pk_mul_f32 v[212:213], v[210:211], v[212:213]
	v_cvt_pk_bf16_f32 v216, v212, v213
	global_store_dword v2, v216, s[66:67]
	s_add_u32 s66, s66, 0x2c00
	s_addc_u32 s67, s67, 0
	s_branch .LBB0_770

; __device__ __forceinline__ float bf2f(unsigned b) { return __uint_as_float(b << 16); }
; __device__ __forceinline__ void act_item(int item, u16* UP, const u16* HALO, const float* sconv, const float* wconv, const float* bconv, float* out, int lane) {
;     const int rb = item / 22, cch = item - rb * 22, j0 = cch * 128 + 2 * lane;
;     float wgt[3][2], wvl[3][2], bg[2], bv[2];
; #pragma unroll
;     for (int k = 0; k < 3; ++k) { const f32x2 a = *(const f32x2*)(wconv + k * FF2 + j0), b = *(const f32x2*)(wconv + k * FF2 + FF + j0); wgt[k][0] = a.x; wgt[k][1] = a.y; wvl[k][0] = b.x; wvl[k][1] = b.y; }
;     { const f32x2 a = *(const f32x2*)(bconv + j0), b = *(const f32x2*)(bconv + FF + j0); bg[0] = a.x; bg[1] = a.y; bv[0] = b.x; bv[1] = b.y; }
;     const bool sample = rb >= 256;
;     float g2[2] = {0.f, 0.f}, g1[2] = {0.f, 0.f}, v2[2] = {0.f, 0.f}, v1[2] = {0.f, 0.f};
;     if (!sample && (rb & 31) != 0) {
;         const unsigned a = *(const unsigned*)(HALO + (size_t)((rb - 1) * 2) * FF2 + j0), b = *(const unsigned*)(HALO + (size_t)((rb - 1) * 2) * FF2 + FF + j0);
;         const unsigned c = *(const unsigned*)(HALO + (size_t)((rb - 1) * 2 + 1) * FF2 + j0), dd = *(const unsigned*)(HALO + (size_t)((rb - 1) * 2 + 1) * FF2 + FF + j0);
;         g2[0] = bf2f(a & 0xffffu); g2[1] = bf2f(a >> 16); v2[0] = bf2f(b & 0xffffu); v2[1] = bf2f(b >> 16);
;         g1[0] = bf2f(c & 0xffffu); g1[1] = bf2f(c >> 16); v1[0] = bf2f(dd & 0xffffu); v1[1] = bf2f(dd >> 16);
;     }
.LBB0_771:
	s_mul_hi_i32 s0, s80, 0x2e8ba2e9
	s_lshr_b32 s1, s0, 31
	s_ashr_i32 s0, s0, 2
	s_add_i32 s0, s0, s1
	s_mul_i32 s1, s0, 0xffffffea
	s_add_i32 s1, s1, s80
	v_lshl_or_b32 v2, s1, 7, v41
	v_ashrrev_i32_e32 v3, 31, v2
	v_lshlrev_b64 v[16:17], 2, v[2:3]
	v_lshl_add_u64 v[4:5], s[42:43], 0, v[16:17]
	v_lshl_add_u64 v[6:7], s[36:37], 0, v[16:17]
	v_lshl_add_u64 v[8:9], s[38:39], 0, v[16:17]
	v_lshl_add_u64 v[10:11], s[40:41], 0, v[16:17]
	global_load_dwordx2 v[4:5], v[4:5], off
	s_nop 0
	global_load_dwordx2 v[6:7], v[6:7], off
	s_nop 0
	global_load_dwordx2 v[8:9], v[8:9], off
	s_nop 0
	global_load_dwordx2 v[10:11], v[10:11], off
	v_lshl_add_u64 v[12:13], s[46:47], 0, v[16:17]
	v_lshl_add_u64 v[14:15], s[54:55], 0, v[16:17]
	v_lshl_add_u64 v[18:19], s[44:45], 0, v[16:17]
	global_load_dwordx2 v[12:13], v[12:13], off
	s_nop 0
	global_load_dwordx2 v[14:15], v[14:15], off
	v_lshl_add_u64 v[20:21], s[56:57], 0, v[16:17]
	global_load_dwordx2 v[16:17], v[18:19], off
	s_nop 0
	global_load_dwordx2 v[18:19], v[20:21], off
	s_cmpk_lt_i32 s80, 0x1600
	s_cbranch_scc1 .Lact_fast
	s_cmpk_gt_i32 s80, 0x15ff
	s_cselect_b64 s[58:59], -1, 0
	s_cmpk_lt_i32 s80, 0x1600
	s_cselect_b64 s[60:61], -1, 0
	s_and_b32 s1, s0, 31
	s_cmp_eq_u32 s1, 0
	s_cselect_b64 s[6:7], -1, 0
	s_or_b64 s[6:7], s[58:59], s[6:7]
	v_mov_b32_e32 v1, v0
	s_and_b64 vcc, exec, s[6:7]
	v_mov_b64_e32 v[50:51], v[0:1]
	v_mov_b64_e32 v[48:49], v[0:1]
	v_mov_b64_e32 v[54:55], v[0:1]
	v_mov_b64_e32 v[52:53], v[0:1]
	s_cbranch_vccnz .LBB0_773
	s_lshl_b32 s62, s0, 1
	s_mul_i32 s7, s0, 0x5800
	s_add_i32 s6, s62, -2
	s_addk_i32 s7, 0xa800
	s_mul_hi_i32 s63, s6, 0x2c00
	s_add_u32 s6, s18, s7
	s_addc_u32 s7, s19, s63
	v_lshlrev_b64 v[20:21], 1, v[2:3]
	v_lshl_add_u64 v[22:23], s[6:7], 0, v[20:21]
	s_add_i32 s6, s62, -1
	s_mul_hi_i32 s7, s6, 0x2c00
	s_mulk_i32 s6, 0x2c00
	s_add_u32 s6, s18, s6
	v_add_co_u32_e32 v24, vcc, 0x1000, v22
	s_addc_u32 s7, s19, s7
	s_nop 0
	v_addc_co_u32_e32 v25, vcc, 0, v23, vcc
	v_lshl_add_u64 v[20:21], s[6:7], 0, v[20:21]
	global_load_dword v1, v[22:23], off
	s_nop 0
	global_load_dword v22, v[24:25], off offset:1536
	global_load_dword v23, v[20:21], off
	v_add_co_u32_e32 v20, vcc, s71, v20
	s_waitcnt vmcnt(0)
	v_lshlrev_b32_e32 v48, 16, v1
	v_addc_co_u32_e32 v21, vcc, 0, v21, vcc
	global_load_dword v20, v[20:21], off offset:1536
	v_and_b32_e32 v49, 0xffff0000, v1
	v_lshlrev_b32_e32 v50, 16, v22
	v_and_b32_e32 v51, 0xffff0000, v22
	v_lshlrev_b32_e32 v52, 16, v23
	v_and_b32_e32 v53, 0xffff0000, v23
	s_waitcnt vmcnt(0)
	v_lshlrev_b32_e32 v54, 16, v20
	v_and_b32_e32 v55, 0xffff0000, v20

; __global__ void __launch_bounds__(512, 2) fwd_kernel(Args args) {
	.amdhsa_kernel _Z10fwd_kernel4Args
		.amdhsa_group_segment_fixed_size 0
		.amdhsa_private_segment_fixed_size 0
		.amdhsa_kernarg_size 496
		.amdhsa_user_sgpr_count 2
		.amdhsa_user_sgpr_dispatch_ptr 0
		.amdhsa_user_sgpr_queue_ptr 0
		.amdhsa_user_sgpr_kernarg_segment_ptr 1
		.amdhsa_user_sgpr_dispatch_id 0
		.amdhsa_user_sgpr_kernarg_preload_length 0
		.amdhsa_user_sgpr_kernarg_preload_offset 0
		.amdhsa_user_sgpr_private_segment_size 0
		.amdhsa_uses_dynamic_stack 0
		.amdhsa_enable_private_segment 0
		.amdhsa_system_sgpr_workgroup_id_x 1
		.amdhsa_system_sgpr_workgroup_id_y 0
		.amdhsa_system_sgpr_workgroup_id_z 0
		.amdhsa_system_sgpr_workgroup_info 0
		.amdhsa_system_vgpr_workitem_id 2
		.amdhsa_next_free_vgpr 256
		.amdhsa_next_free_sgpr 102
		.amdhsa_accum_offset 256
		.amdhsa_reserve_vcc 1
		.amdhsa_float_round_mode_32 0
		.amdhsa_float_round_mode_16_64 0
		.amdhsa_float_denorm_mode_32 3
		.amdhsa_float_denorm_mode_16_64 3
		.amdhsa_dx10_clamp 1
		.amdhsa_ieee_mode 1
		.amdhsa_fp16_overflow 0
		.amdhsa_tg_split 0
		.amdhsa_exception_fp_ieee_invalid_op 0
		.amdhsa_exception_fp_denorm_src 0
		.amdhsa_exception_fp_ieee_div_zero 0
		.amdhsa_exception_fp_ieee_overflow 0
		.amdhsa_exception_fp_ieee_underflow 0
		.amdhsa_exception_fp_ieee_inexact 0
		.amdhsa_exception_int_div_zero 0
	.end_amdhsa_kernel

; __global__ void __launch_bounds__(512, 2) fwd_kernel(Args args) {
amdhsa.kernels:
  - .agpr_count:     0
    .args:
      - .offset:         0
        .size:           240
        .value_kind:     by_value
      - .offset:         240
        .size:           4
        .value_kind:     hidden_block_count_x
      - .offset:         244
        .size:           4
        .value_kind:     hidden_block_count_y
      - .offset:         248
        .size:           4
        .value_kind:     hidden_block_count_z
      - .offset:         252
        .size:           2
        .value_kind:     hidden_group_size_x
      - .offset:         254
        .size:           2
        .value_kind:     hidden_group_size_y
      - .offset:         256
        .size:           2
        .value_kind:     hidden_group_size_z
      - .offset:         258
        .size:           2
        .value_kind:     hidden_remainder_x
      - .offset:         260
        .size:           2
        .value_kind:     hidden_remainder_y
      - .offset:         262
        .size:           2
        .value_kind:     hidden_remainder_z
      - .offset:         280
        .size:           8
        .value_kind:     hidden_global_offset_x
      - .offset:         288
        .size:           8
        .value_kind:     hidden_global_offset_y
      - .offset:         296
        .size:           8
        .value_kind:     hidden_global_offset_z
      - .offset:         304
        .size:           2
        .value_kind:     hidden_grid_dims
      - .offset:         328
        .size:           8
        .value_kind:     hidden_multigrid_sync_arg
      - .offset:         360
        .size:           4
        .value_kind:     hidden_dynamic_lds_size
    .group_segment_fixed_size: 0
    .kernarg_segment_align: 8
    .kernarg_segment_size: 496
    .language:       OpenCL C
    .language_version:
      - 2
      - 0
    .max_flat_workgroup_size: 512
    .name:           _Z10fwd_kernel4Args
    .private_segment_fixed_size: 0
    .sgpr_count:     108
    .sgpr_spill_count: 74
    .symbol:         _Z10fwd_kernel4Args.kd
    .uniform_work_group_size: 1
    .uses_dynamic_stack: false
    .vgpr_count:     256
    .vgpr_spill_count: 0
    .wavefront_size: 64
